# K-loops: the s_nop after each m0 write replaced by placing the address v_lshl_add_u64 between the m0 write and the LDS-DMA load (58 issue slots fewer)
# speedup vs baseline: 1.0046x; 1.0021x over previous
.LBB0_233:
	v_mov_b64_e32 v[0:1], 0x5a0
	s_ashr_i32 s95, s94, 31
	v_cmp_lt_i64_e32 vcc, s[34:35], v[0:1]
	s_lshl_b64 s[34:35], s[94:95], 20
	s_add_u32 s96, s56, s34
	s_addc_u32 s97, s57, s35
	s_and_b64 s[34:35], vcc, exec
	s_cselect_b32 s9, s97, s11
	s_cselect_b32 s89, s96, s10
	s_ashr_i32 s71, s70, 31
	s_lshl_b64 s[34:35], s[70:71], 20
	s_add_u32 s98, s82, s34
	s_addc_u32 s99, s83, s35
	s_and_b64 s[34:35], vcc, exec
	s_cselect_b32 s71, s99, s29
	s_cselect_b32 s91, s98, s28
	s_add_u32 s10, s10, 0x80080
	s_addc_u32 s11, s11, 0
	s_add_u32 s93, s28, 0x100
	s_addc_u32 s95, s29, 0
	s_mov_b32 vcc_lo, -2
	ds_read_b128 v[136:139], v167
	ds_read_b128 v[140:143], v167 offset:1024
	ds_read_b128 v[144:147], v167 offset:2048
	ds_read_b128 v[148:151], v167 offset:3072
	s_add_u32 s3, s10, 0xfff80080
	s_addc_u32 s28, s11, -1
	s_cmp_eq_u32 vcc_lo, 28
	s_cselect_b32 s35, s9, s28
	s_cselect_b32 s34, s89, s3
	s_cselect_b32 s29, s71, s95
	s_cselect_b32 s28, s91, s93
	v_lshl_add_u64 v[152:153], s[10:11], 0, v[132:133]
	s_add_i32 m0, s62, 0xc000
	ds_read_b128 v[172:175], v168
	ds_read_b128 v[190:193], v168 offset:1024
	ds_read_b128 v[194:197], v168 offset:2048
	ds_read_b128 v[198:201], v168 offset:3072
	ds_read_b128 v[202:205], v168 offset:4096
	ds_read_b128 v[206:209], v168 offset:5120
	ds_read_b128 v[224:227], v168 offset:6144
	ds_read_b128 v[228:231], v168 offset:7168
	global_load_lds_dwordx4 v[152:153], off
	s_add_i32 m0, s62, 0xe000
	v_lshl_add_u64 v[152:153], s[10:11], 0, v[134:135]
	global_load_lds_dwordx4 v[152:153], off
	s_waitcnt lgkmcnt(8)
	s_barrier
	s_waitcnt lgkmcnt(0)
	v_mfma_f32_16x16x32_bf16 v[124:127], v[136:139], v[172:175], 0
	v_mfma_f32_16x16x32_bf16 v[116:119], v[144:147], v[172:175], 0
	v_mfma_f32_16x16x32_bf16 v[108:111], v[136:139], v[194:197], 0
	v_mfma_f32_16x16x32_bf16 v[100:103], v[144:147], v[194:197], 0
	v_mfma_f32_16x16x32_bf16 v[92:95], v[136:139], v[202:205], 0
	v_mfma_f32_16x16x32_bf16 v[84:87], v[144:147], v[202:205], 0
	v_mfma_f32_16x16x32_bf16 v[76:79], v[136:139], v[224:227], 0
	v_mfma_f32_16x16x32_bf16 v[68:71], v[144:147], v[224:227], 0
	v_mfma_f32_16x16x32_bf16 v[124:127], v[140:143], v[190:193], v[124:127]
	v_mfma_f32_16x16x32_bf16 v[116:119], v[148:151], v[190:193], v[116:119]
	v_mfma_f32_16x16x32_bf16 v[108:111], v[140:143], v[198:201], v[108:111]
	v_mfma_f32_16x16x32_bf16 v[100:103], v[148:151], v[198:201], v[100:103]
	v_mfma_f32_16x16x32_bf16 v[92:95], v[140:143], v[206:209], v[92:95]
	v_mfma_f32_16x16x32_bf16 v[84:87], v[148:151], v[206:209], v[84:87]
	v_mfma_f32_16x16x32_bf16 v[76:79], v[140:143], v[228:231], v[76:79]
	v_mfma_f32_16x16x32_bf16 v[68:71], v[148:151], v[228:231], v[68:71]
	s_barrier
	s_add_i32 s3, s84, s61
	v_lshl_add_u64 v[152:153], s[28:29], 0, v[184:185]
	s_mov_b32 m0, s3
	ds_read_b128 v[232:235], v169
	ds_read_b128 v[236:239], v169 offset:1024
	ds_read_b128 v[240:243], v169 offset:2048
	ds_read_b128 v[244:247], v169 offset:3072
	global_load_lds_dwordx4 v[152:153], off
	s_add_i32 m0, s3, 0x2000
	v_lshl_add_u64 v[248:249], s[28:29], 0, v[188:189]
	global_load_lds_dwordx4 v[248:249], off
	s_barrier
	s_waitcnt lgkmcnt(0)
	v_mfma_f32_16x16x32_bf16 v[120:123], v[232:235], v[172:175], 0
	v_mfma_f32_16x16x32_bf16 v[112:115], v[240:243], v[172:175], 0
	v_mfma_f32_16x16x32_bf16 v[104:107], v[232:235], v[194:197], 0
	v_mfma_f32_16x16x32_bf16 v[96:99], v[240:243], v[194:197], 0
	v_mfma_f32_16x16x32_bf16 v[88:91], v[232:235], v[202:205], 0
	v_mfma_f32_16x16x32_bf16 v[80:83], v[240:243], v[202:205], 0
	v_mfma_f32_16x16x32_bf16 v[72:75], v[232:235], v[224:227], 0
	v_mfma_f32_16x16x32_bf16 v[64:67], v[240:243], v[224:227], 0
	v_mfma_f32_16x16x32_bf16 v[120:123], v[236:239], v[190:193], v[120:123]
	v_mfma_f32_16x16x32_bf16 v[112:115], v[244:247], v[190:193], v[112:115]
	v_mfma_f32_16x16x32_bf16 v[104:107], v[236:239], v[198:201], v[104:107]
	v_mfma_f32_16x16x32_bf16 v[96:99], v[244:247], v[198:201], v[96:99]
	v_mfma_f32_16x16x32_bf16 v[88:91], v[236:239], v[206:209], v[88:91]
	v_mfma_f32_16x16x32_bf16 v[80:83], v[244:247], v[206:209], v[80:83]
	v_mfma_f32_16x16x32_bf16 v[72:75], v[236:239], v[228:231], v[72:75]
	v_mfma_f32_16x16x32_bf16 v[64:67], v[244:247], v[228:231], v[64:67]
	s_mov_b32 m0, s62
	v_lshl_add_u64 v[250:251], s[34:35], 0, v[182:183]
	s_barrier
	ds_read_b128 v[172:175], v168 offset:16384
	ds_read_b128 v[190:193], v168 offset:17408
	ds_read_b128 v[194:197], v168 offset:18432
	ds_read_b128 v[198:201], v168 offset:19456
	ds_read_b128 v[202:205], v168 offset:20480
	ds_read_b128 v[206:209], v168 offset:21504
	ds_read_b128 v[224:227], v168 offset:22528
	ds_read_b128 v[228:231], v168 offset:23552
	global_load_lds_dwordx4 v[250:251], off
	s_mov_b32 m0, s63
	v_lshl_add_u64 v[252:253], s[34:35], 0, v[186:187]
	global_load_lds_dwordx4 v[252:253], off
	s_barrier
	s_waitcnt lgkmcnt(0)
	v_mfma_f32_16x16x32_bf16 v[60:63], v[136:139], v[172:175], 0
	v_mfma_f32_16x16x32_bf16 v[52:55], v[144:147], v[172:175], 0
	v_mfma_f32_16x16x32_bf16 v[44:47], v[136:139], v[194:197], 0
	v_mfma_f32_16x16x32_bf16 v[36:39], v[144:147], v[194:197], 0
	v_mfma_f32_16x16x32_bf16 v[28:31], v[136:139], v[202:205], 0
	v_mfma_f32_16x16x32_bf16 v[20:23], v[144:147], v[202:205], 0
	v_mfma_f32_16x16x32_bf16 v[12:15], v[136:139], v[224:227], 0
	v_mfma_f32_16x16x32_bf16 v[4:7], v[144:147], v[224:227], 0
	v_mfma_f32_16x16x32_bf16 v[60:63], v[140:143], v[190:193], v[60:63]
	v_mfma_f32_16x16x32_bf16 v[52:55], v[148:151], v[190:193], v[52:55]
	v_mfma_f32_16x16x32_bf16 v[44:47], v[140:143], v[198:201], v[44:47]
	v_mfma_f32_16x16x32_bf16 v[36:39], v[148:151], v[198:201], v[36:39]
	v_mfma_f32_16x16x32_bf16 v[28:31], v[140:143], v[206:209], v[28:31]
	v_mfma_f32_16x16x32_bf16 v[20:23], v[148:151], v[206:209], v[20:23]
	v_mfma_f32_16x16x32_bf16 v[12:15], v[140:143], v[228:231], v[12:15]
	v_mfma_f32_16x16x32_bf16 v[4:7], v[148:151], v[228:231], v[4:7]
	s_barrier
	s_add_u32 s74, s28, 0x80000
	s_addc_u32 s75, s29, 0
	s_add_i32 s3, s85, s61
	s_mov_b32 m0, s3
	v_lshl_add_u64 v[136:137], s[74:75], 0, v[184:185]
	global_load_lds_dwordx4 v[136:137], off
	s_add_i32 m0, s3, 0x2000
	v_lshl_add_u64 v[136:137], s[74:75], 0, v[188:189]
	global_load_lds_dwordx4 v[136:137], off
	s_waitcnt vmcnt(6)
	s_barrier
	v_mfma_f32_16x16x32_bf16 v[56:59], v[232:235], v[172:175], 0
	v_mfma_f32_16x16x32_bf16 v[48:51], v[240:243], v[172:175], 0
	v_mfma_f32_16x16x32_bf16 v[40:43], v[232:235], v[194:197], 0
	v_mfma_f32_16x16x32_bf16 v[32:35], v[240:243], v[194:197], 0
	v_mfma_f32_16x16x32_bf16 v[24:27], v[232:235], v[202:205], 0
	v_mfma_f32_16x16x32_bf16 v[16:19], v[240:243], v[202:205], 0
	v_mfma_f32_16x16x32_bf16 v[8:11], v[232:235], v[224:227], 0
	v_mfma_f32_16x16x32_bf16 v[0:3], v[240:243], v[224:227], 0
	v_mfma_f32_16x16x32_bf16 v[56:59], v[236:239], v[190:193], v[56:59]
	v_mfma_f32_16x16x32_bf16 v[48:51], v[244:247], v[190:193], v[48:51]
	v_mfma_f32_16x16x32_bf16 v[40:43], v[236:239], v[198:201], v[40:43]
	v_mfma_f32_16x16x32_bf16 v[32:35], v[244:247], v[198:201], v[32:35]
	v_mfma_f32_16x16x32_bf16 v[24:27], v[236:239], v[206:209], v[24:27]
	v_mfma_f32_16x16x32_bf16 v[16:19], v[244:247], v[206:209], v[16:19]
	v_mfma_f32_16x16x32_bf16 v[8:11], v[236:239], v[228:231], v[8:11]
	v_mfma_f32_16x16x32_bf16 v[0:3], v[244:247], v[228:231], v[0:3]
	s_add_i32 s3, 0, 0x18000
	v_add_u32_e32 v130, s3, v165
	s_barrier
	ds_read_b128 v[136:139], v130
	ds_read_b128 v[140:143], v130 offset:1024
	ds_read_b128 v[144:147], v130 offset:2048
	ds_read_b128 v[148:151], v130 offset:3072
	s_add_u32 s34, s34, 0x80000
	s_addc_u32 s35, s35, 0
	s_mov_b32 m0, s64
	v_lshl_add_u64 v[232:233], s[34:35], 0, v[182:183]
	ds_read_b128 v[172:175], v168 offset:32768
	ds_read_b128 v[190:193], v168 offset:33792
	ds_read_b128 v[194:197], v168 offset:34816
	ds_read_b128 v[198:201], v168 offset:35840
	ds_read_b128 v[202:205], v168 offset:36864
	ds_read_b128 v[206:209], v168 offset:37888
	ds_read_b128 v[224:227], v168 offset:38912
	ds_read_b128 v[228:231], v168 offset:39936
	global_load_lds_dwordx4 v[232:233], off
	s_mov_b32 m0, s65
	v_lshl_add_u64 v[232:233], s[34:35], 0, v[186:187]
	global_load_lds_dwordx4 v[232:233], off
	s_waitcnt lgkmcnt(8)
	s_barrier
	s_waitcnt lgkmcnt(0)
	v_mfma_f32_16x16x32_bf16 v[124:127], v[136:139], v[172:175], v[124:127]
	v_mfma_f32_16x16x32_bf16 v[116:119], v[144:147], v[172:175], v[116:119]
	v_mfma_f32_16x16x32_bf16 v[108:111], v[136:139], v[194:197], v[108:111]
	v_mfma_f32_16x16x32_bf16 v[100:103], v[144:147], v[194:197], v[100:103]
	v_mfma_f32_16x16x32_bf16 v[92:95], v[136:139], v[202:205], v[92:95]
	v_mfma_f32_16x16x32_bf16 v[84:87], v[144:147], v[202:205], v[84:87]
	v_mfma_f32_16x16x32_bf16 v[76:79], v[136:139], v[224:227], v[76:79]
	v_mfma_f32_16x16x32_bf16 v[68:71], v[144:147], v[224:227], v[68:71]
	v_mfma_f32_16x16x32_bf16 v[124:127], v[140:143], v[190:193], v[124:127]
	v_mfma_f32_16x16x32_bf16 v[116:119], v[148:151], v[190:193], v[116:119]
	v_mfma_f32_16x16x32_bf16 v[108:111], v[140:143], v[198:201], v[108:111]
	v_mfma_f32_16x16x32_bf16 v[100:103], v[148:151], v[198:201], v[100:103]
	v_mfma_f32_16x16x32_bf16 v[92:95], v[140:143], v[206:209], v[92:95]
	v_mfma_f32_16x16x32_bf16 v[84:87], v[148:151], v[206:209], v[84:87]
	v_mfma_f32_16x16x32_bf16 v[76:79], v[140:143], v[228:231], v[76:79]
	v_mfma_f32_16x16x32_bf16 v[68:71], v[148:151], v[228:231], v[68:71]
	s_barrier
	s_add_i32 s33, 0, 0x1c000
	s_add_i32 s3, s3, s61
	v_add_u32_e32 v130, s33, v165
	v_lshl_add_u64 v[152:153], v[152:153], 0, s[86:87]
	s_mov_b32 m0, s3
	ds_read_b128 v[232:235], v130
	ds_read_b128 v[236:239], v130 offset:1024
	ds_read_b128 v[240:243], v130 offset:2048
	ds_read_b128 v[244:247], v130 offset:3072
	global_load_lds_dwordx4 v[152:153], off
	s_add_i32 m0, s3, 0x2000
	v_lshl_add_u64 v[152:153], v[248:249], 0, s[86:87]
	global_load_lds_dwordx4 v[152:153], off
	s_barrier
	s_waitcnt lgkmcnt(0)
	v_mfma_f32_16x16x32_bf16 v[120:123], v[232:235], v[172:175], v[120:123]
	v_mfma_f32_16x16x32_bf16 v[112:115], v[240:243], v[172:175], v[112:115]
	v_mfma_f32_16x16x32_bf16 v[104:107], v[232:235], v[194:197], v[104:107]
	v_mfma_f32_16x16x32_bf16 v[96:99], v[240:243], v[194:197], v[96:99]
	v_mfma_f32_16x16x32_bf16 v[88:91], v[232:235], v[202:205], v[88:91]
	v_mfma_f32_16x16x32_bf16 v[80:83], v[240:243], v[202:205], v[80:83]
	v_mfma_f32_16x16x32_bf16 v[72:75], v[232:235], v[224:227], v[72:75]
	v_mfma_f32_16x16x32_bf16 v[64:67], v[240:243], v[224:227], v[64:67]
	v_mfma_f32_16x16x32_bf16 v[120:123], v[236:239], v[190:193], v[120:123]
	v_mfma_f32_16x16x32_bf16 v[112:115], v[244:247], v[190:193], v[112:115]
	v_mfma_f32_16x16x32_bf16 v[104:107], v[236:239], v[198:201], v[104:107]
	v_mfma_f32_16x16x32_bf16 v[96:99], v[244:247], v[198:201], v[96:99]
	v_mfma_f32_16x16x32_bf16 v[88:91], v[236:239], v[206:209], v[88:91]
	v_mfma_f32_16x16x32_bf16 v[80:83], v[244:247], v[206:209], v[80:83]
	v_mfma_f32_16x16x32_bf16 v[72:75], v[236:239], v[228:231], v[72:75]
	v_mfma_f32_16x16x32_bf16 v[64:67], v[244:247], v[228:231], v[64:67]
	s_mov_b32 m0, s67
	v_lshl_add_u64 v[152:153], v[250:251], 0, s[86:87]
	s_barrier
	ds_read_b128 v[172:175], v168 offset:49152
	ds_read_b128 v[190:193], v168 offset:50176
	ds_read_b128 v[194:197], v168 offset:51200
	ds_read_b128 v[198:201], v168 offset:52224
	ds_read_b128 v[202:205], v168 offset:53248
	ds_read_b128 v[206:209], v168 offset:54272
	ds_read_b128 v[224:227], v168 offset:55296
	ds_read_b128 v[228:231], v168 offset:56320
	global_load_lds_dwordx4 v[152:153], off
	s_mov_b32 m0, s68
	v_lshl_add_u64 v[152:153], v[252:253], 0, s[86:87]
	global_load_lds_dwordx4 v[152:153], off
	s_barrier
	s_waitcnt lgkmcnt(0)
	v_mfma_f32_16x16x32_bf16 v[60:63], v[136:139], v[172:175], v[60:63]
	v_mfma_f32_16x16x32_bf16 v[52:55], v[144:147], v[172:175], v[52:55]
	v_mfma_f32_16x16x32_bf16 v[44:47], v[136:139], v[194:197], v[44:47]
	v_mfma_f32_16x16x32_bf16 v[36:39], v[144:147], v[194:197], v[36:39]
	v_mfma_f32_16x16x32_bf16 v[28:31], v[136:139], v[202:205], v[28:31]
	v_mfma_f32_16x16x32_bf16 v[20:23], v[144:147], v[202:205], v[20:23]
	v_mfma_f32_16x16x32_bf16 v[12:15], v[136:139], v[224:227], v[12:15]
	v_mfma_f32_16x16x32_bf16 v[4:7], v[144:147], v[224:227], v[4:7]
	v_mfma_f32_16x16x32_bf16 v[60:63], v[140:143], v[190:193], v[60:63]
	v_mfma_f32_16x16x32_bf16 v[52:55], v[148:151], v[190:193], v[52:55]
	v_mfma_f32_16x16x32_bf16 v[44:47], v[140:143], v[198:201], v[44:47]
	v_mfma_f32_16x16x32_bf16 v[36:39], v[148:151], v[198:201], v[36:39]
	v_mfma_f32_16x16x32_bf16 v[28:31], v[140:143], v[206:209], v[28:31]
	v_mfma_f32_16x16x32_bf16 v[20:23], v[148:151], v[206:209], v[20:23]
	v_mfma_f32_16x16x32_bf16 v[12:15], v[140:143], v[228:231], v[12:15]
	v_mfma_f32_16x16x32_bf16 v[4:7], v[148:151], v[228:231], v[4:7]
	s_barrier
	s_add_u32 s28, s28, 0x80080
	s_addc_u32 s29, s29, 0
	s_add_i32 s3, s33, s61
	s_mov_b32 m0, s3
	v_lshl_add_u64 v[136:137], s[28:29], 0, v[184:185]
	global_load_lds_dwordx4 v[136:137], off
	s_add_i32 m0, s3, 0x2000
	v_lshl_add_u64 v[136:137], s[28:29], 0, v[188:189]
	global_load_lds_dwordx4 v[136:137], off
	s_waitcnt vmcnt(6)
	s_barrier
	v_mfma_f32_16x16x32_bf16 v[56:59], v[232:235], v[172:175], v[56:59]
	v_mfma_f32_16x16x32_bf16 v[48:51], v[240:243], v[172:175], v[48:51]
	v_mfma_f32_16x16x32_bf16 v[40:43], v[232:235], v[194:197], v[40:43]
	v_mfma_f32_16x16x32_bf16 v[32:35], v[240:243], v[194:197], v[32:35]
	v_mfma_f32_16x16x32_bf16 v[24:27], v[232:235], v[202:205], v[24:27]
	v_mfma_f32_16x16x32_bf16 v[16:19], v[240:243], v[202:205], v[16:19]
	v_mfma_f32_16x16x32_bf16 v[8:11], v[232:235], v[224:227], v[8:11]
	v_mfma_f32_16x16x32_bf16 v[0:3], v[240:243], v[224:227], v[0:3]
	v_mfma_f32_16x16x32_bf16 v[56:59], v[236:239], v[190:193], v[56:59]
	v_mfma_f32_16x16x32_bf16 v[48:51], v[244:247], v[190:193], v[48:51]
	v_mfma_f32_16x16x32_bf16 v[40:43], v[236:239], v[198:201], v[40:43]
	v_mfma_f32_16x16x32_bf16 v[32:35], v[244:247], v[198:201], v[32:35]
	v_mfma_f32_16x16x32_bf16 v[24:27], v[236:239], v[206:209], v[24:27]
	v_mfma_f32_16x16x32_bf16 v[16:19], v[244:247], v[206:209], v[16:19]
	v_mfma_f32_16x16x32_bf16 v[8:11], v[236:239], v[228:231], v[8:11]
	v_mfma_f32_16x16x32_bf16 v[0:3], v[244:247], v[228:231], v[0:3]
	s_add_i32 vcc_lo, vcc_lo, 2
	s_add_u32 s10, s10, 0x100
	s_addc_u32 s11, s11, 0
	s_add_u32 s93, s93, 0x100
	s_addc_u32 s95, s95, 0
	s_cmp_gt_u32 vcc_lo, 29
	s_barrier
	s_cbranch_scc1 .Lpeel_done_in
.LBB0_234:
	ds_read_b128 v[136:139], v167
	ds_read_b128 v[140:143], v167 offset:1024
	ds_read_b128 v[144:147], v167 offset:2048
	ds_read_b128 v[148:151], v167 offset:3072
	s_add_u32 s3, s10, 0xfff80080
	s_addc_u32 s28, s11, -1
	s_cmp_eq_u32 vcc_lo, 28
	s_cselect_b32 s35, s9, s28
	s_cselect_b32 s34, s89, s3
	s_cselect_b32 s29, s71, s95
	s_cselect_b32 s28, s91, s93
	v_lshl_add_u64 v[152:153], s[10:11], 0, v[132:133]
	s_add_i32 m0, s62, 0xc000
	ds_read_b128 v[172:175], v168
	ds_read_b128 v[190:193], v168 offset:1024
	ds_read_b128 v[194:197], v168 offset:2048
	ds_read_b128 v[198:201], v168 offset:3072
	ds_read_b128 v[202:205], v168 offset:4096
	ds_read_b128 v[206:209], v168 offset:5120
	ds_read_b128 v[224:227], v168 offset:6144
	ds_read_b128 v[228:231], v168 offset:7168
	global_load_lds_dwordx4 v[152:153], off
	s_add_i32 m0, s62, 0xe000
	v_lshl_add_u64 v[152:153], s[10:11], 0, v[134:135]
	global_load_lds_dwordx4 v[152:153], off
	s_waitcnt lgkmcnt(8)
	s_barrier
	s_waitcnt lgkmcnt(0)
	v_mfma_f32_16x16x32_bf16 v[124:127], v[136:139], v[172:175], v[124:127]
	v_mfma_f32_16x16x32_bf16 v[116:119], v[144:147], v[172:175], v[116:119]
	v_mfma_f32_16x16x32_bf16 v[108:111], v[136:139], v[194:197], v[108:111]
	v_mfma_f32_16x16x32_bf16 v[100:103], v[144:147], v[194:197], v[100:103]
	v_mfma_f32_16x16x32_bf16 v[92:95], v[136:139], v[202:205], v[92:95]
	v_mfma_f32_16x16x32_bf16 v[84:87], v[144:147], v[202:205], v[84:87]
	v_mfma_f32_16x16x32_bf16 v[76:79], v[136:139], v[224:227], v[76:79]
	v_mfma_f32_16x16x32_bf16 v[68:71], v[144:147], v[224:227], v[68:71]
	v_mfma_f32_16x16x32_bf16 v[124:127], v[140:143], v[190:193], v[124:127]
	v_mfma_f32_16x16x32_bf16 v[116:119], v[148:151], v[190:193], v[116:119]
	v_mfma_f32_16x16x32_bf16 v[108:111], v[140:143], v[198:201], v[108:111]
	v_mfma_f32_16x16x32_bf16 v[100:103], v[148:151], v[198:201], v[100:103]
	v_mfma_f32_16x16x32_bf16 v[92:95], v[140:143], v[206:209], v[92:95]
	v_mfma_f32_16x16x32_bf16 v[84:87], v[148:151], v[206:209], v[84:87]
	v_mfma_f32_16x16x32_bf16 v[76:79], v[140:143], v[228:231], v[76:79]
	v_mfma_f32_16x16x32_bf16 v[68:71], v[148:151], v[228:231], v[68:71]
	s_barrier
	s_add_i32 s3, s84, s61
	v_lshl_add_u64 v[152:153], s[28:29], 0, v[184:185]
	s_mov_b32 m0, s3
	ds_read_b128 v[232:235], v169
	ds_read_b128 v[236:239], v169 offset:1024
	ds_read_b128 v[240:243], v169 offset:2048
	ds_read_b128 v[244:247], v169 offset:3072
	global_load_lds_dwordx4 v[152:153], off
	s_add_i32 m0, s3, 0x2000
	v_lshl_add_u64 v[248:249], s[28:29], 0, v[188:189]
	global_load_lds_dwordx4 v[248:249], off
	s_barrier
	s_waitcnt lgkmcnt(0)
	v_mfma_f32_16x16x32_bf16 v[120:123], v[232:235], v[172:175], v[120:123]
	v_mfma_f32_16x16x32_bf16 v[112:115], v[240:243], v[172:175], v[112:115]
	v_mfma_f32_16x16x32_bf16 v[104:107], v[232:235], v[194:197], v[104:107]
	v_mfma_f32_16x16x32_bf16 v[96:99], v[240:243], v[194:197], v[96:99]
	v_mfma_f32_16x16x32_bf16 v[88:91], v[232:235], v[202:205], v[88:91]
	v_mfma_f32_16x16x32_bf16 v[80:83], v[240:243], v[202:205], v[80:83]
	v_mfma_f32_16x16x32_bf16 v[72:75], v[232:235], v[224:227], v[72:75]
	v_mfma_f32_16x16x32_bf16 v[64:67], v[240:243], v[224:227], v[64:67]
	v_mfma_f32_16x16x32_bf16 v[120:123], v[236:239], v[190:193], v[120:123]
	v_mfma_f32_16x16x32_bf16 v[112:115], v[244:247], v[190:193], v[112:115]
	v_mfma_f32_16x16x32_bf16 v[104:107], v[236:239], v[198:201], v[104:107]
	v_mfma_f32_16x16x32_bf16 v[96:99], v[244:247], v[198:201], v[96:99]
	v_mfma_f32_16x16x32_bf16 v[88:91], v[236:239], v[206:209], v[88:91]
	v_mfma_f32_16x16x32_bf16 v[80:83], v[244:247], v[206:209], v[80:83]
	v_mfma_f32_16x16x32_bf16 v[72:75], v[236:239], v[228:231], v[72:75]
	v_mfma_f32_16x16x32_bf16 v[64:67], v[244:247], v[228:231], v[64:67]
	s_mov_b32 m0, s62
	v_lshl_add_u64 v[250:251], s[34:35], 0, v[182:183]
	s_barrier
	ds_read_b128 v[172:175], v168 offset:16384
	ds_read_b128 v[190:193], v168 offset:17408
	ds_read_b128 v[194:197], v168 offset:18432
	ds_read_b128 v[198:201], v168 offset:19456
	ds_read_b128 v[202:205], v168 offset:20480
	ds_read_b128 v[206:209], v168 offset:21504
	ds_read_b128 v[224:227], v168 offset:22528
	ds_read_b128 v[228:231], v168 offset:23552
	global_load_lds_dwordx4 v[250:251], off
	s_mov_b32 m0, s63
	v_lshl_add_u64 v[252:253], s[34:35], 0, v[186:187]
	global_load_lds_dwordx4 v[252:253], off
	s_barrier
	s_waitcnt lgkmcnt(0)
	v_mfma_f32_16x16x32_bf16 v[60:63], v[136:139], v[172:175], v[60:63]
	v_mfma_f32_16x16x32_bf16 v[52:55], v[144:147], v[172:175], v[52:55]
	v_mfma_f32_16x16x32_bf16 v[44:47], v[136:139], v[194:197], v[44:47]
	v_mfma_f32_16x16x32_bf16 v[36:39], v[144:147], v[194:197], v[36:39]
	v_mfma_f32_16x16x32_bf16 v[28:31], v[136:139], v[202:205], v[28:31]
	v_mfma_f32_16x16x32_bf16 v[20:23], v[144:147], v[202:205], v[20:23]
	v_mfma_f32_16x16x32_bf16 v[12:15], v[136:139], v[224:227], v[12:15]
	v_mfma_f32_16x16x32_bf16 v[4:7], v[144:147], v[224:227], v[4:7]
	v_mfma_f32_16x16x32_bf16 v[60:63], v[140:143], v[190:193], v[60:63]
	v_mfma_f32_16x16x32_bf16 v[52:55], v[148:151], v[190:193], v[52:55]
	v_mfma_f32_16x16x32_bf16 v[44:47], v[140:143], v[198:201], v[44:47]
	v_mfma_f32_16x16x32_bf16 v[36:39], v[148:151], v[198:201], v[36:39]
	v_mfma_f32_16x16x32_bf16 v[28:31], v[140:143], v[206:209], v[28:31]
	v_mfma_f32_16x16x32_bf16 v[20:23], v[148:151], v[206:209], v[20:23]
	v_mfma_f32_16x16x32_bf16 v[12:15], v[140:143], v[228:231], v[12:15]
	v_mfma_f32_16x16x32_bf16 v[4:7], v[148:151], v[228:231], v[4:7]
	s_barrier
	s_add_u32 s74, s28, 0x80000
	s_addc_u32 s75, s29, 0
	s_add_i32 s3, s85, s61
	s_mov_b32 m0, s3
	v_lshl_add_u64 v[136:137], s[74:75], 0, v[184:185]
	global_load_lds_dwordx4 v[136:137], off
	s_add_i32 m0, s3, 0x2000
	v_lshl_add_u64 v[136:137], s[74:75], 0, v[188:189]
	global_load_lds_dwordx4 v[136:137], off
	s_waitcnt vmcnt(6)
	s_barrier
	v_mfma_f32_16x16x32_bf16 v[56:59], v[232:235], v[172:175], v[56:59]
	v_mfma_f32_16x16x32_bf16 v[48:51], v[240:243], v[172:175], v[48:51]
	v_mfma_f32_16x16x32_bf16 v[40:43], v[232:235], v[194:197], v[40:43]
	v_mfma_f32_16x16x32_bf16 v[32:35], v[240:243], v[194:197], v[32:35]
	v_mfma_f32_16x16x32_bf16 v[24:27], v[232:235], v[202:205], v[24:27]
	v_mfma_f32_16x16x32_bf16 v[16:19], v[240:243], v[202:205], v[16:19]
	v_mfma_f32_16x16x32_bf16 v[8:11], v[232:235], v[224:227], v[8:11]
	v_mfma_f32_16x16x32_bf16 v[0:3], v[240:243], v[224:227], v[0:3]
	v_mfma_f32_16x16x32_bf16 v[56:59], v[236:239], v[190:193], v[56:59]
	v_mfma_f32_16x16x32_bf16 v[48:51], v[244:247], v[190:193], v[48:51]
	v_mfma_f32_16x16x32_bf16 v[40:43], v[236:239], v[198:201], v[40:43]
	v_mfma_f32_16x16x32_bf16 v[32:35], v[244:247], v[198:201], v[32:35]
	v_mfma_f32_16x16x32_bf16 v[24:27], v[236:239], v[206:209], v[24:27]
	v_mfma_f32_16x16x32_bf16 v[16:19], v[244:247], v[206:209], v[16:19]
	v_mfma_f32_16x16x32_bf16 v[8:11], v[236:239], v[228:231], v[8:11]
	v_mfma_f32_16x16x32_bf16 v[0:3], v[244:247], v[228:231], v[0:3]
	s_add_i32 s3, 0, 0x18000
	v_add_u32_e32 v130, s3, v165
	s_barrier
	ds_read_b128 v[136:139], v130
	ds_read_b128 v[140:143], v130 offset:1024
	ds_read_b128 v[144:147], v130 offset:2048
	ds_read_b128 v[148:151], v130 offset:3072
	s_add_u32 s34, s34, 0x80000
	s_addc_u32 s35, s35, 0
	s_mov_b32 m0, s64
	v_lshl_add_u64 v[232:233], s[34:35], 0, v[182:183]
	ds_read_b128 v[172:175], v168 offset:32768
	ds_read_b128 v[190:193], v168 offset:33792
	ds_read_b128 v[194:197], v168 offset:34816
	ds_read_b128 v[198:201], v168 offset:35840
	ds_read_b128 v[202:205], v168 offset:36864
	ds_read_b128 v[206:209], v168 offset:37888
	ds_read_b128 v[224:227], v168 offset:38912
	ds_read_b128 v[228:231], v168 offset:39936
	global_load_lds_dwordx4 v[232:233], off
	s_mov_b32 m0, s65
	v_lshl_add_u64 v[232:233], s[34:35], 0, v[186:187]
	global_load_lds_dwordx4 v[232:233], off
	s_waitcnt lgkmcnt(8)
	s_barrier
	s_waitcnt lgkmcnt(0)
	v_mfma_f32_16x16x32_bf16 v[124:127], v[136:139], v[172:175], v[124:127]
	v_mfma_f32_16x16x32_bf16 v[116:119], v[144:147], v[172:175], v[116:119]
	v_mfma_f32_16x16x32_bf16 v[108:111], v[136:139], v[194:197], v[108:111]
	v_mfma_f32_16x16x32_bf16 v[100:103], v[144:147], v[194:197], v[100:103]
	v_mfma_f32_16x16x32_bf16 v[92:95], v[136:139], v[202:205], v[92:95]
	v_mfma_f32_16x16x32_bf16 v[84:87], v[144:147], v[202:205], v[84:87]
	v_mfma_f32_16x16x32_bf16 v[76:79], v[136:139], v[224:227], v[76:79]
	v_mfma_f32_16x16x32_bf16 v[68:71], v[144:147], v[224:227], v[68:71]
	v_mfma_f32_16x16x32_bf16 v[124:127], v[140:143], v[190:193], v[124:127]
	v_mfma_f32_16x16x32_bf16 v[116:119], v[148:151], v[190:193], v[116:119]
	v_mfma_f32_16x16x32_bf16 v[108:111], v[140:143], v[198:201], v[108:111]
	v_mfma_f32_16x16x32_bf16 v[100:103], v[148:151], v[198:201], v[100:103]
	v_mfma_f32_16x16x32_bf16 v[92:95], v[140:143], v[206:209], v[92:95]
	v_mfma_f32_16x16x32_bf16 v[84:87], v[148:151], v[206:209], v[84:87]
	v_mfma_f32_16x16x32_bf16 v[76:79], v[140:143], v[228:231], v[76:79]
	v_mfma_f32_16x16x32_bf16 v[68:71], v[148:151], v[228:231], v[68:71]
	s_barrier
	s_add_i32 s33, 0, 0x1c000
	s_add_i32 s3, s3, s61
	v_add_u32_e32 v130, s33, v165
	v_lshl_add_u64 v[152:153], v[152:153], 0, s[86:87]
	s_mov_b32 m0, s3
	ds_read_b128 v[232:235], v130
	ds_read_b128 v[236:239], v130 offset:1024
	ds_read_b128 v[240:243], v130 offset:2048
	ds_read_b128 v[244:247], v130 offset:3072
	global_load_lds_dwordx4 v[152:153], off
	s_add_i32 m0, s3, 0x2000
	v_lshl_add_u64 v[152:153], v[248:249], 0, s[86:87]
	global_load_lds_dwordx4 v[152:153], off
	s_barrier
	s_waitcnt lgkmcnt(0)
	v_mfma_f32_16x16x32_bf16 v[120:123], v[232:235], v[172:175], v[120:123]
	v_mfma_f32_16x16x32_bf16 v[112:115], v[240:243], v[172:175], v[112:115]
	v_mfma_f32_16x16x32_bf16 v[104:107], v[232:235], v[194:197], v[104:107]
	v_mfma_f32_16x16x32_bf16 v[96:99], v[240:243], v[194:197], v[96:99]
	v_mfma_f32_16x16x32_bf16 v[88:91], v[232:235], v[202:205], v[88:91]
	v_mfma_f32_16x16x32_bf16 v[80:83], v[240:243], v[202:205], v[80:83]
	v_mfma_f32_16x16x32_bf16 v[72:75], v[232:235], v[224:227], v[72:75]
	v_mfma_f32_16x16x32_bf16 v[64:67], v[240:243], v[224:227], v[64:67]
	v_mfma_f32_16x16x32_bf16 v[120:123], v[236:239], v[190:193], v[120:123]
	v_mfma_f32_16x16x32_bf16 v[112:115], v[244:247], v[190:193], v[112:115]
	v_mfma_f32_16x16x32_bf16 v[104:107], v[236:239], v[198:201], v[104:107]
	v_mfma_f32_16x16x32_bf16 v[96:99], v[244:247], v[198:201], v[96:99]
	v_mfma_f32_16x16x32_bf16 v[88:91], v[236:239], v[206:209], v[88:91]
	v_mfma_f32_16x16x32_bf16 v[80:83], v[244:247], v[206:209], v[80:83]
	v_mfma_f32_16x16x32_bf16 v[72:75], v[236:239], v[228:231], v[72:75]
	v_mfma_f32_16x16x32_bf16 v[64:67], v[244:247], v[228:231], v[64:67]
	s_mov_b32 m0, s67
	v_lshl_add_u64 v[152:153], v[250:251], 0, s[86:87]
	s_barrier
	ds_read_b128 v[172:175], v168 offset:49152
	ds_read_b128 v[190:193], v168 offset:50176
	ds_read_b128 v[194:197], v168 offset:51200
	ds_read_b128 v[198:201], v168 offset:52224
	ds_read_b128 v[202:205], v168 offset:53248
	ds_read_b128 v[206:209], v168 offset:54272
	ds_read_b128 v[224:227], v168 offset:55296
	ds_read_b128 v[228:231], v168 offset:56320
	global_load_lds_dwordx4 v[152:153], off
	s_mov_b32 m0, s68
	v_lshl_add_u64 v[152:153], v[252:253], 0, s[86:87]
	global_load_lds_dwordx4 v[152:153], off
	s_barrier
	s_waitcnt lgkmcnt(0)
	v_mfma_f32_16x16x32_bf16 v[60:63], v[136:139], v[172:175], v[60:63]
	v_mfma_f32_16x16x32_bf16 v[52:55], v[144:147], v[172:175], v[52:55]
	v_mfma_f32_16x16x32_bf16 v[44:47], v[136:139], v[194:197], v[44:47]
	v_mfma_f32_16x16x32_bf16 v[36:39], v[144:147], v[194:197], v[36:39]
	v_mfma_f32_16x16x32_bf16 v[28:31], v[136:139], v[202:205], v[28:31]
	v_mfma_f32_16x16x32_bf16 v[20:23], v[144:147], v[202:205], v[20:23]
	v_mfma_f32_16x16x32_bf16 v[12:15], v[136:139], v[224:227], v[12:15]
	v_mfma_f32_16x16x32_bf16 v[4:7], v[144:147], v[224:227], v[4:7]
	v_mfma_f32_16x16x32_bf16 v[60:63], v[140:143], v[190:193], v[60:63]
	v_mfma_f32_16x16x32_bf16 v[52:55], v[148:151], v[190:193], v[52:55]
	v_mfma_f32_16x16x32_bf16 v[44:47], v[140:143], v[198:201], v[44:47]
	v_mfma_f32_16x16x32_bf16 v[36:39], v[148:151], v[198:201], v[36:39]
	v_mfma_f32_16x16x32_bf16 v[28:31], v[140:143], v[206:209], v[28:31]
	v_mfma_f32_16x16x32_bf16 v[20:23], v[148:151], v[206:209], v[20:23]
	v_mfma_f32_16x16x32_bf16 v[12:15], v[140:143], v[228:231], v[12:15]
	v_mfma_f32_16x16x32_bf16 v[4:7], v[148:151], v[228:231], v[4:7]
	s_barrier
	s_add_u32 s28, s28, 0x80080
	s_addc_u32 s29, s29, 0
	s_add_i32 s3, s33, s61
	s_mov_b32 m0, s3
	v_lshl_add_u64 v[136:137], s[28:29], 0, v[184:185]
	global_load_lds_dwordx4 v[136:137], off
	s_add_i32 m0, s3, 0x2000
	v_lshl_add_u64 v[136:137], s[28:29], 0, v[188:189]
	global_load_lds_dwordx4 v[136:137], off
	s_waitcnt vmcnt(6)
	s_barrier
	v_mfma_f32_16x16x32_bf16 v[56:59], v[232:235], v[172:175], v[56:59]
	v_mfma_f32_16x16x32_bf16 v[48:51], v[240:243], v[172:175], v[48:51]
	v_mfma_f32_16x16x32_bf16 v[40:43], v[232:235], v[194:197], v[40:43]
	v_mfma_f32_16x16x32_bf16 v[32:35], v[240:243], v[194:197], v[32:35]
	v_mfma_f32_16x16x32_bf16 v[24:27], v[232:235], v[202:205], v[24:27]
	v_mfma_f32_16x16x32_bf16 v[16:19], v[240:243], v[202:205], v[16:19]
	v_mfma_f32_16x16x32_bf16 v[8:11], v[232:235], v[224:227], v[8:11]
	v_mfma_f32_16x16x32_bf16 v[0:3], v[240:243], v[224:227], v[0:3]
	v_mfma_f32_16x16x32_bf16 v[56:59], v[236:239], v[190:193], v[56:59]
	v_mfma_f32_16x16x32_bf16 v[48:51], v[244:247], v[190:193], v[48:51]
	v_mfma_f32_16x16x32_bf16 v[40:43], v[236:239], v[198:201], v[40:43]
	v_mfma_f32_16x16x32_bf16 v[32:35], v[244:247], v[198:201], v[32:35]
	v_mfma_f32_16x16x32_bf16 v[24:27], v[236:239], v[206:209], v[24:27]
	v_mfma_f32_16x16x32_bf16 v[16:19], v[244:247], v[206:209], v[16:19]
	v_mfma_f32_16x16x32_bf16 v[8:11], v[236:239], v[228:231], v[8:11]
	v_mfma_f32_16x16x32_bf16 v[0:3], v[244:247], v[228:231], v[0:3]
	s_add_i32 vcc_lo, vcc_lo, 2
	s_add_u32 s10, s10, 0x100
	s_addc_u32 s11, s11, 0
	s_add_u32 s93, s93, 0x100
	s_addc_u32 s95, s95, 0
	s_cmp_gt_u32 vcc_lo, 29
	s_barrier
	s_cbranch_scc0 .LBB0_234

.LBB0_557:
	s_ashr_i32 s41, s40, 31
	s_xor_b64 s[44:45], s[34:35], -1
	s_lshl_b64 s[46:47], s[40:41], 20
	s_add_u32 s3, s8, s46
	s_addc_u32 s39, s9, s47
	s_ashr_i32 s43, s42, 31
	s_lshl_b64 s[48:49], s[42:43], 1
	s_add_u32 s46, s3, s48
	s_addc_u32 s47, s39, s49
	s_and_b64 s[50:51], s[34:35], exec
	s_cselect_b32 s41, s47, s11
	s_cselect_b32 s43, s46, s10
	s_ashr_i32 s39, s38, 31
	s_lshl_b64 s[50:51], s[38:39], 20
	s_add_u32 s3, s72, s50
	s_addc_u32 s39, s73, s51
	s_add_u32 s48, s3, s48
	s_addc_u32 s49, s39, s49
	s_and_b64 s[34:35], s[34:35], exec
	s_cselect_b32 s39, s49, s29
	s_cselect_b32 s50, s48, s28
	s_add_u32 s10, s10, 0x80080
	s_addc_u32 s11, s11, 0
	s_add_u32 s51, s28, 0x100
	s_addc_u32 s85, s29, 0
	s_mov_b32 s86, 2
	ds_read_b128 v[40:43], v228
	ds_read_b128 v[44:47], v228 offset:1024
	ds_read_b128 v[52:55], v228 offset:2048
	ds_read_b128 v[60:63], v228 offset:3072
	s_add_u32 s3, s10, 0xfff80080
	s_addc_u32 s28, s11, -1
	s_cmp_eq_u32 s84, s86
	s_cselect_b32 s35, s41, s28
	s_cselect_b32 s34, s43, s3
	s_cselect_b32 s29, s39, s85
	s_cselect_b32 s28, s50, s51
	v_lshl_add_u64 v[198:199], s[10:11], 0, v[192:193]
	s_add_i32 m0, s61, 0xc000
	ds_read_b128 v[144:147], v229
	ds_read_b128 v[148:151], v229 offset:1024
	ds_read_b128 v[152:155], v229 offset:2048
	ds_read_b128 v[156:159], v229 offset:3072
	ds_read_b128 v[160:163], v229 offset:4096
	ds_read_b128 v[164:167], v229 offset:5120
	ds_read_b128 v[168:171], v229 offset:6144
	ds_read_b128 v[172:175], v229 offset:7168
	global_load_lds_dwordx4 v[198:199], off
	s_add_i32 m0, s61, 0xe000
	v_lshl_add_u64 v[198:199], s[10:11], 0, v[194:195]
	global_load_lds_dwordx4 v[198:199], off
	s_waitcnt lgkmcnt(8)
	s_barrier
	s_waitcnt lgkmcnt(0)
	v_mfma_f32_16x16x32_bf16 v[140:143], v[40:43], v[144:147], 0
	v_mfma_f32_16x16x32_bf16 v[136:139], v[52:55], v[144:147], 0
	v_mfma_f32_16x16x32_bf16 v[124:127], v[40:43], v[152:155], 0
	v_mfma_f32_16x16x32_bf16 v[120:123], v[52:55], v[152:155], 0
	v_mfma_f32_16x16x32_bf16 v[108:111], v[40:43], v[160:163], 0
	v_mfma_f32_16x16x32_bf16 v[104:107], v[52:55], v[160:163], 0
	v_mfma_f32_16x16x32_bf16 v[92:95], v[40:43], v[168:171], 0
	v_mfma_f32_16x16x32_bf16 v[88:91], v[52:55], v[168:171], 0
	v_mfma_f32_16x16x32_bf16 v[140:143], v[44:47], v[148:151], v[140:143]
	v_mfma_f32_16x16x32_bf16 v[136:139], v[60:63], v[148:151], v[136:139]
	v_mfma_f32_16x16x32_bf16 v[124:127], v[44:47], v[156:159], v[124:127]
	v_mfma_f32_16x16x32_bf16 v[120:123], v[60:63], v[156:159], v[120:123]
	v_mfma_f32_16x16x32_bf16 v[108:111], v[44:47], v[164:167], v[108:111]
	v_mfma_f32_16x16x32_bf16 v[104:107], v[60:63], v[164:167], v[104:107]
	v_mfma_f32_16x16x32_bf16 v[92:95], v[44:47], v[172:175], v[92:95]
	v_mfma_f32_16x16x32_bf16 v[88:91], v[60:63], v[172:175], v[88:91]
	s_barrier
	s_add_i32 s3, s79, s69
	v_lshl_add_u64 v[236:237], s[28:29], 0, v[184:185]
	s_mov_b32 m0, s3
	ds_read_b128 v[198:201], v230
	ds_read_b128 v[202:205], v230 offset:1024
	ds_read_b128 v[206:209], v230 offset:2048
	ds_read_b128 v[232:235], v230 offset:3072
	global_load_lds_dwordx4 v[236:237], off
	s_add_i32 m0, s3, 0x2000
	v_lshl_add_u64 v[238:239], s[28:29], 0, v[188:189]
	global_load_lds_dwordx4 v[238:239], off
	s_barrier
	s_waitcnt lgkmcnt(0)
	v_mfma_f32_16x16x32_bf16 v[132:135], v[198:201], v[144:147], 0
	v_mfma_f32_16x16x32_bf16 v[128:131], v[206:209], v[144:147], 0
	v_mfma_f32_16x16x32_bf16 v[116:119], v[198:201], v[152:155], 0
	v_mfma_f32_16x16x32_bf16 v[112:115], v[206:209], v[152:155], 0
	v_mfma_f32_16x16x32_bf16 v[100:103], v[198:201], v[160:163], 0
	v_mfma_f32_16x16x32_bf16 v[96:99], v[206:209], v[160:163], 0
	v_mfma_f32_16x16x32_bf16 v[84:87], v[198:201], v[168:171], 0
	v_mfma_f32_16x16x32_bf16 v[80:83], v[206:209], v[168:171], 0
	v_mfma_f32_16x16x32_bf16 v[132:135], v[202:205], v[148:151], v[132:135]
	v_mfma_f32_16x16x32_bf16 v[128:131], v[232:235], v[148:151], v[128:131]
	v_mfma_f32_16x16x32_bf16 v[116:119], v[202:205], v[156:159], v[116:119]
	v_mfma_f32_16x16x32_bf16 v[112:115], v[232:235], v[156:159], v[112:115]
	v_mfma_f32_16x16x32_bf16 v[100:103], v[202:205], v[164:167], v[100:103]
	v_mfma_f32_16x16x32_bf16 v[96:99], v[232:235], v[164:167], v[96:99]
	v_mfma_f32_16x16x32_bf16 v[84:87], v[202:205], v[172:175], v[84:87]
	v_mfma_f32_16x16x32_bf16 v[80:83], v[232:235], v[172:175], v[80:83]
	s_mov_b32 m0, s61
	v_lshl_add_u64 v[240:241], s[34:35], 0, v[182:183]
	s_barrier
	ds_read_b128 v[144:147], v229 offset:16384
	ds_read_b128 v[148:151], v229 offset:17408
	ds_read_b128 v[152:155], v229 offset:18432
	ds_read_b128 v[156:159], v229 offset:19456
	ds_read_b128 v[160:163], v229 offset:20480
	ds_read_b128 v[164:167], v229 offset:21504
	ds_read_b128 v[168:171], v229 offset:22528
	ds_read_b128 v[172:175], v229 offset:23552
	global_load_lds_dwordx4 v[240:241], off
	s_mov_b32 m0, s63
	v_lshl_add_u64 v[242:243], s[34:35], 0, v[186:187]
	global_load_lds_dwordx4 v[242:243], off
	s_barrier
	s_waitcnt lgkmcnt(0)
	v_mfma_f32_16x16x32_bf16 v[76:79], v[40:43], v[144:147], 0
	v_mfma_f32_16x16x32_bf16 v[72:75], v[52:55], v[144:147], 0
	v_mfma_f32_16x16x32_bf16 v[56:59], v[40:43], v[152:155], 0
	v_mfma_f32_16x16x32_bf16 v[48:51], v[52:55], v[152:155], 0
	v_mfma_f32_16x16x32_bf16 v[28:31], v[40:43], v[160:163], 0
	v_mfma_f32_16x16x32_bf16 v[24:27], v[52:55], v[160:163], 0
	v_mfma_f32_16x16x32_bf16 v[12:15], v[40:43], v[168:171], 0
	v_mfma_f32_16x16x32_bf16 v[8:11], v[52:55], v[168:171], 0
	v_mfma_f32_16x16x32_bf16 v[76:79], v[44:47], v[148:151], v[76:79]
	v_mfma_f32_16x16x32_bf16 v[72:75], v[60:63], v[148:151], v[72:75]
	v_mfma_f32_16x16x32_bf16 v[56:59], v[44:47], v[156:159], v[56:59]
	v_mfma_f32_16x16x32_bf16 v[48:51], v[60:63], v[156:159], v[48:51]
	v_mfma_f32_16x16x32_bf16 v[28:31], v[44:47], v[164:167], v[28:31]
	v_mfma_f32_16x16x32_bf16 v[24:27], v[60:63], v[164:167], v[24:27]
	v_mfma_f32_16x16x32_bf16 v[12:15], v[44:47], v[172:175], v[12:15]
	v_mfma_f32_16x16x32_bf16 v[8:11], v[60:63], v[172:175], v[8:11]
	s_barrier
	s_add_u32 s88, s28, 0x80000
	s_addc_u32 s89, s29, 0
	s_add_i32 s3, s80, s69
	s_mov_b32 m0, s3
	v_lshl_add_u64 v[40:41], s[88:89], 0, v[184:185]
	global_load_lds_dwordx4 v[40:41], off
	s_add_i32 m0, s3, 0x2000
	v_lshl_add_u64 v[40:41], s[88:89], 0, v[188:189]
	global_load_lds_dwordx4 v[40:41], off
	s_waitcnt vmcnt(6)
	s_barrier
	v_mfma_f32_16x16x32_bf16 v[36:39], v[198:201], v[152:155], 0
	v_mfma_f32_16x16x32_bf16 v[32:35], v[206:209], v[152:155], 0
	v_mfma_f32_16x16x32_bf16 v[20:23], v[198:201], v[160:163], 0
	v_mfma_f32_16x16x32_bf16 v[16:19], v[206:209], v[160:163], 0
	v_mfma_f32_16x16x32_bf16 v[4:7], v[198:201], v[168:171], 0
	v_mfma_f32_16x16x32_bf16 v[0:3], v[206:209], v[168:171], 0
	v_mfma_f32_16x16x32_bf16 v[40:43], v[198:201], v[144:147], 0
	v_mfma_f32_16x16x32_bf16 v[44:47], v[206:209], v[144:147], 0
	v_mfma_f32_16x16x32_bf16 v[36:39], v[202:205], v[156:159], v[36:39]
	v_mfma_f32_16x16x32_bf16 v[32:35], v[232:235], v[156:159], v[32:35]
	v_mfma_f32_16x16x32_bf16 v[20:23], v[202:205], v[164:167], v[20:23]
	v_mfma_f32_16x16x32_bf16 v[16:19], v[232:235], v[164:167], v[16:19]
	v_mfma_f32_16x16x32_bf16 v[4:7], v[202:205], v[172:175], v[4:7]
	v_mfma_f32_16x16x32_bf16 v[0:3], v[232:235], v[172:175], v[0:3]
	v_mfma_f32_16x16x32_bf16 v[40:43], v[202:205], v[148:151], v[40:43]
	v_mfma_f32_16x16x32_bf16 v[44:47], v[232:235], v[148:151], v[44:47]
	s_add_i32 s3, 0, 0x18000
	v_add_u32_e32 v68, s3, v226
	s_barrier
	ds_read_b128 v[52:55], v68
	ds_read_b128 v[60:63], v68 offset:1024
	ds_read_b128 v[64:67], v68 offset:2048
	ds_read_b128 v[68:71], v68 offset:3072
	s_add_u32 s34, s34, 0x80000
	s_addc_u32 s35, s35, 0
	s_mov_b32 m0, s67
	v_lshl_add_u64 v[198:199], s[34:35], 0, v[182:183]
	ds_read_b128 v[144:147], v229 offset:32768
	ds_read_b128 v[148:151], v229 offset:33792
	ds_read_b128 v[152:155], v229 offset:34816
	ds_read_b128 v[156:159], v229 offset:35840
	ds_read_b128 v[160:163], v229 offset:36864
	ds_read_b128 v[164:167], v229 offset:37888
	ds_read_b128 v[168:171], v229 offset:38912
	ds_read_b128 v[172:175], v229 offset:39936
	global_load_lds_dwordx4 v[198:199], off
	s_mov_b32 m0, s70
	v_lshl_add_u64 v[198:199], s[34:35], 0, v[186:187]
	global_load_lds_dwordx4 v[198:199], off
	s_waitcnt lgkmcnt(8)
	s_barrier
	s_waitcnt lgkmcnt(0)
	v_mfma_f32_16x16x32_bf16 v[140:143], v[52:55], v[144:147], v[140:143]
	v_mfma_f32_16x16x32_bf16 v[136:139], v[64:67], v[144:147], v[136:139]
	v_mfma_f32_16x16x32_bf16 v[124:127], v[52:55], v[152:155], v[124:127]
	v_mfma_f32_16x16x32_bf16 v[120:123], v[64:67], v[152:155], v[120:123]
	v_mfma_f32_16x16x32_bf16 v[108:111], v[52:55], v[160:163], v[108:111]
	v_mfma_f32_16x16x32_bf16 v[104:107], v[64:67], v[160:163], v[104:107]
	v_mfma_f32_16x16x32_bf16 v[92:95], v[52:55], v[168:171], v[92:95]
	v_mfma_f32_16x16x32_bf16 v[88:91], v[64:67], v[168:171], v[88:91]
	v_mfma_f32_16x16x32_bf16 v[140:143], v[60:63], v[148:151], v[140:143]
	v_mfma_f32_16x16x32_bf16 v[136:139], v[68:71], v[148:151], v[136:139]
	v_mfma_f32_16x16x32_bf16 v[124:127], v[60:63], v[156:159], v[124:127]
	v_mfma_f32_16x16x32_bf16 v[120:123], v[68:71], v[156:159], v[120:123]
	v_mfma_f32_16x16x32_bf16 v[108:111], v[60:63], v[164:167], v[108:111]
	v_mfma_f32_16x16x32_bf16 v[104:107], v[68:71], v[164:167], v[104:107]
	v_mfma_f32_16x16x32_bf16 v[92:95], v[60:63], v[172:175], v[92:95]
	v_mfma_f32_16x16x32_bf16 v[88:91], v[68:71], v[172:175], v[88:91]
	s_barrier
	s_add_i32 s34, 0, 0x1c000
	s_add_i32 s3, s3, s69
	v_add_u32_e32 v231, s34, v226
	v_lshl_add_u64 v[236:237], v[236:237], 0, s[22:23]
	s_mov_b32 m0, s3
	ds_read_b128 v[198:201], v231
	ds_read_b128 v[202:205], v231 offset:1024
	ds_read_b128 v[206:209], v231 offset:2048
	ds_read_b128 v[232:235], v231 offset:3072
	global_load_lds_dwordx4 v[236:237], off
	s_add_i32 m0, s3, 0x2000
	v_lshl_add_u64 v[236:237], v[238:239], 0, s[22:23]
	global_load_lds_dwordx4 v[236:237], off
	s_barrier
	s_waitcnt lgkmcnt(0)
	v_mfma_f32_16x16x32_bf16 v[132:135], v[198:201], v[144:147], v[132:135]
	v_mfma_f32_16x16x32_bf16 v[128:131], v[206:209], v[144:147], v[128:131]
	v_mfma_f32_16x16x32_bf16 v[116:119], v[198:201], v[152:155], v[116:119]
	v_mfma_f32_16x16x32_bf16 v[112:115], v[206:209], v[152:155], v[112:115]
	v_mfma_f32_16x16x32_bf16 v[100:103], v[198:201], v[160:163], v[100:103]
	v_mfma_f32_16x16x32_bf16 v[96:99], v[206:209], v[160:163], v[96:99]
	v_mfma_f32_16x16x32_bf16 v[84:87], v[198:201], v[168:171], v[84:87]
	v_mfma_f32_16x16x32_bf16 v[80:83], v[206:209], v[168:171], v[80:83]
	v_mfma_f32_16x16x32_bf16 v[132:135], v[202:205], v[148:151], v[132:135]
	v_mfma_f32_16x16x32_bf16 v[128:131], v[232:235], v[148:151], v[128:131]
	v_mfma_f32_16x16x32_bf16 v[116:119], v[202:205], v[156:159], v[116:119]
	v_mfma_f32_16x16x32_bf16 v[112:115], v[232:235], v[156:159], v[112:115]
	v_mfma_f32_16x16x32_bf16 v[100:103], v[202:205], v[164:167], v[100:103]
	v_mfma_f32_16x16x32_bf16 v[96:99], v[232:235], v[164:167], v[96:99]
	v_mfma_f32_16x16x32_bf16 v[84:87], v[202:205], v[172:175], v[84:87]
	v_mfma_f32_16x16x32_bf16 v[80:83], v[232:235], v[172:175], v[80:83]
	s_mov_b32 m0, s71
	v_lshl_add_u64 v[236:237], v[240:241], 0, s[22:23]
	s_barrier
	ds_read_b128 v[144:147], v229 offset:49152
	ds_read_b128 v[148:151], v229 offset:50176
	ds_read_b128 v[152:155], v229 offset:51200
	ds_read_b128 v[156:159], v229 offset:52224
	ds_read_b128 v[160:163], v229 offset:53248
	ds_read_b128 v[164:167], v229 offset:54272
	ds_read_b128 v[168:171], v229 offset:55296
	ds_read_b128 v[172:175], v229 offset:56320
	global_load_lds_dwordx4 v[236:237], off
	s_mov_b32 m0, s74
	v_lshl_add_u64 v[236:237], v[242:243], 0, s[22:23]
	global_load_lds_dwordx4 v[236:237], off
	s_barrier
	s_waitcnt lgkmcnt(0)
	v_mfma_f32_16x16x32_bf16 v[76:79], v[52:55], v[144:147], v[76:79]
	v_mfma_f32_16x16x32_bf16 v[72:75], v[64:67], v[144:147], v[72:75]
	v_mfma_f32_16x16x32_bf16 v[56:59], v[52:55], v[152:155], v[56:59]
	v_mfma_f32_16x16x32_bf16 v[48:51], v[64:67], v[152:155], v[48:51]
	v_mfma_f32_16x16x32_bf16 v[28:31], v[52:55], v[160:163], v[28:31]
	v_mfma_f32_16x16x32_bf16 v[24:27], v[64:67], v[160:163], v[24:27]
	v_mfma_f32_16x16x32_bf16 v[12:15], v[52:55], v[168:171], v[12:15]
	v_mfma_f32_16x16x32_bf16 v[8:11], v[64:67], v[168:171], v[8:11]
	v_mfma_f32_16x16x32_bf16 v[76:79], v[60:63], v[148:151], v[76:79]
	v_mfma_f32_16x16x32_bf16 v[72:75], v[68:71], v[148:151], v[72:75]
	v_mfma_f32_16x16x32_bf16 v[56:59], v[60:63], v[156:159], v[56:59]
	v_mfma_f32_16x16x32_bf16 v[48:51], v[68:71], v[156:159], v[48:51]
	v_mfma_f32_16x16x32_bf16 v[28:31], v[60:63], v[164:167], v[28:31]
	v_mfma_f32_16x16x32_bf16 v[24:27], v[68:71], v[164:167], v[24:27]
	v_mfma_f32_16x16x32_bf16 v[12:15], v[60:63], v[172:175], v[12:15]
	v_mfma_f32_16x16x32_bf16 v[8:11], v[68:71], v[172:175], v[8:11]
	s_barrier
	s_add_u32 s28, s28, 0x80080
	s_addc_u32 s29, s29, 0
	s_add_i32 s3, s34, s69
	s_mov_b32 m0, s3
	v_lshl_add_u64 v[52:53], s[28:29], 0, v[184:185]
	global_load_lds_dwordx4 v[52:53], off
	s_add_i32 m0, s3, 0x2000
	v_lshl_add_u64 v[52:53], s[28:29], 0, v[188:189]
	global_load_lds_dwordx4 v[52:53], off
	s_waitcnt vmcnt(6)
	s_barrier
	v_mfma_f32_16x16x32_bf16 v[40:43], v[198:201], v[144:147], v[40:43]
	v_mfma_f32_16x16x32_bf16 v[68:71], v[202:205], v[148:151], v[40:43]
	v_mfma_f32_16x16x32_bf16 v[40:43], v[206:209], v[144:147], v[44:47]
	v_mfma_f32_16x16x32_bf16 v[36:39], v[198:201], v[152:155], v[36:39]
	v_mfma_f32_16x16x32_bf16 v[32:35], v[206:209], v[152:155], v[32:35]
	v_mfma_f32_16x16x32_bf16 v[20:23], v[198:201], v[160:163], v[20:23]
	v_mfma_f32_16x16x32_bf16 v[16:19], v[206:209], v[160:163], v[16:19]
	v_mfma_f32_16x16x32_bf16 v[4:7], v[198:201], v[168:171], v[4:7]
	v_mfma_f32_16x16x32_bf16 v[0:3], v[206:209], v[168:171], v[0:3]
	v_mfma_f32_16x16x32_bf16 v[64:67], v[232:235], v[148:151], v[40:43]
	v_mfma_f32_16x16x32_bf16 v[36:39], v[202:205], v[156:159], v[36:39]
	v_mfma_f32_16x16x32_bf16 v[32:35], v[232:235], v[156:159], v[32:35]
	v_mfma_f32_16x16x32_bf16 v[20:23], v[202:205], v[164:167], v[20:23]
	v_mfma_f32_16x16x32_bf16 v[16:19], v[232:235], v[164:167], v[16:19]
	v_mfma_f32_16x16x32_bf16 v[4:7], v[202:205], v[172:175], v[4:7]
	v_mfma_f32_16x16x32_bf16 v[0:3], v[232:235], v[172:175], v[0:3]
	s_add_i32 s3, s86, 2
	s_add_u32 s10, s10, 0x100
	s_addc_u32 s11, s11, 0
	s_add_u32 s51, s51, 0x100
	s_addc_u32 s85, s85, 0
	s_cmp_ge_u32 s86, s84
	s_mov_b32 s86, s3
	s_barrier
	s_cbranch_scc1 .Lpeel_done_glu
.LBB0_558:
	ds_read_b128 v[40:43], v228
	ds_read_b128 v[44:47], v228 offset:1024
	ds_read_b128 v[52:55], v228 offset:2048
	ds_read_b128 v[60:63], v228 offset:3072
	s_add_u32 s3, s10, 0xfff80080
	s_addc_u32 s28, s11, -1
	s_cmp_eq_u32 s84, s86
	s_cselect_b32 s35, s41, s28
	s_cselect_b32 s34, s43, s3
	s_cselect_b32 s29, s39, s85
	s_cselect_b32 s28, s50, s51
	v_lshl_add_u64 v[198:199], s[10:11], 0, v[192:193]
	s_add_i32 m0, s61, 0xc000
	ds_read_b128 v[144:147], v229
	ds_read_b128 v[148:151], v229 offset:1024
	ds_read_b128 v[152:155], v229 offset:2048
	ds_read_b128 v[156:159], v229 offset:3072
	ds_read_b128 v[160:163], v229 offset:4096
	ds_read_b128 v[164:167], v229 offset:5120
	ds_read_b128 v[168:171], v229 offset:6144
	ds_read_b128 v[172:175], v229 offset:7168
	global_load_lds_dwordx4 v[198:199], off
	s_add_i32 m0, s61, 0xe000
	v_lshl_add_u64 v[198:199], s[10:11], 0, v[194:195]
	global_load_lds_dwordx4 v[198:199], off
	s_waitcnt lgkmcnt(8)
	s_barrier
	s_waitcnt lgkmcnt(0)
	v_mfma_f32_16x16x32_bf16 v[140:143], v[40:43], v[144:147], v[140:143]
	v_mfma_f32_16x16x32_bf16 v[136:139], v[52:55], v[144:147], v[136:139]
	v_mfma_f32_16x16x32_bf16 v[124:127], v[40:43], v[152:155], v[124:127]
	v_mfma_f32_16x16x32_bf16 v[120:123], v[52:55], v[152:155], v[120:123]
	v_mfma_f32_16x16x32_bf16 v[108:111], v[40:43], v[160:163], v[108:111]
	v_mfma_f32_16x16x32_bf16 v[104:107], v[52:55], v[160:163], v[104:107]
	v_mfma_f32_16x16x32_bf16 v[92:95], v[40:43], v[168:171], v[92:95]
	v_mfma_f32_16x16x32_bf16 v[88:91], v[52:55], v[168:171], v[88:91]
	v_mfma_f32_16x16x32_bf16 v[140:143], v[44:47], v[148:151], v[140:143]
	v_mfma_f32_16x16x32_bf16 v[136:139], v[60:63], v[148:151], v[136:139]
	v_mfma_f32_16x16x32_bf16 v[124:127], v[44:47], v[156:159], v[124:127]
	v_mfma_f32_16x16x32_bf16 v[120:123], v[60:63], v[156:159], v[120:123]
	v_mfma_f32_16x16x32_bf16 v[108:111], v[44:47], v[164:167], v[108:111]
	v_mfma_f32_16x16x32_bf16 v[104:107], v[60:63], v[164:167], v[104:107]
	v_mfma_f32_16x16x32_bf16 v[92:95], v[44:47], v[172:175], v[92:95]
	v_mfma_f32_16x16x32_bf16 v[88:91], v[60:63], v[172:175], v[88:91]
	s_barrier
	s_add_i32 s3, s79, s69
	v_lshl_add_u64 v[236:237], s[28:29], 0, v[184:185]
	s_mov_b32 m0, s3
	ds_read_b128 v[198:201], v230
	ds_read_b128 v[202:205], v230 offset:1024
	ds_read_b128 v[206:209], v230 offset:2048
	ds_read_b128 v[232:235], v230 offset:3072
	global_load_lds_dwordx4 v[236:237], off
	s_add_i32 m0, s3, 0x2000
	v_lshl_add_u64 v[238:239], s[28:29], 0, v[188:189]
	global_load_lds_dwordx4 v[238:239], off
	s_barrier
	s_waitcnt lgkmcnt(0)
	v_mfma_f32_16x16x32_bf16 v[132:135], v[198:201], v[144:147], v[132:135]
	v_mfma_f32_16x16x32_bf16 v[128:131], v[206:209], v[144:147], v[128:131]
	v_mfma_f32_16x16x32_bf16 v[116:119], v[198:201], v[152:155], v[116:119]
	v_mfma_f32_16x16x32_bf16 v[112:115], v[206:209], v[152:155], v[112:115]
	v_mfma_f32_16x16x32_bf16 v[100:103], v[198:201], v[160:163], v[100:103]
	v_mfma_f32_16x16x32_bf16 v[96:99], v[206:209], v[160:163], v[96:99]
	v_mfma_f32_16x16x32_bf16 v[84:87], v[198:201], v[168:171], v[84:87]
	v_mfma_f32_16x16x32_bf16 v[80:83], v[206:209], v[168:171], v[80:83]
	v_mfma_f32_16x16x32_bf16 v[132:135], v[202:205], v[148:151], v[132:135]
	v_mfma_f32_16x16x32_bf16 v[128:131], v[232:235], v[148:151], v[128:131]
	v_mfma_f32_16x16x32_bf16 v[116:119], v[202:205], v[156:159], v[116:119]
	v_mfma_f32_16x16x32_bf16 v[112:115], v[232:235], v[156:159], v[112:115]
	v_mfma_f32_16x16x32_bf16 v[100:103], v[202:205], v[164:167], v[100:103]
	v_mfma_f32_16x16x32_bf16 v[96:99], v[232:235], v[164:167], v[96:99]
	v_mfma_f32_16x16x32_bf16 v[84:87], v[202:205], v[172:175], v[84:87]
	v_mfma_f32_16x16x32_bf16 v[80:83], v[232:235], v[172:175], v[80:83]
	s_mov_b32 m0, s61
	v_lshl_add_u64 v[240:241], s[34:35], 0, v[182:183]
	s_barrier
	ds_read_b128 v[144:147], v229 offset:16384
	ds_read_b128 v[148:151], v229 offset:17408
	ds_read_b128 v[152:155], v229 offset:18432
	ds_read_b128 v[156:159], v229 offset:19456
	ds_read_b128 v[160:163], v229 offset:20480
	ds_read_b128 v[164:167], v229 offset:21504
	ds_read_b128 v[168:171], v229 offset:22528
	ds_read_b128 v[172:175], v229 offset:23552
	global_load_lds_dwordx4 v[240:241], off
	s_mov_b32 m0, s63
	v_lshl_add_u64 v[242:243], s[34:35], 0, v[186:187]
	global_load_lds_dwordx4 v[242:243], off
	s_barrier
	s_waitcnt lgkmcnt(0)
	v_mfma_f32_16x16x32_bf16 v[76:79], v[40:43], v[144:147], v[76:79]
	v_mfma_f32_16x16x32_bf16 v[72:75], v[52:55], v[144:147], v[72:75]
	v_mfma_f32_16x16x32_bf16 v[56:59], v[40:43], v[152:155], v[56:59]
	v_mfma_f32_16x16x32_bf16 v[48:51], v[52:55], v[152:155], v[48:51]
	v_mfma_f32_16x16x32_bf16 v[28:31], v[40:43], v[160:163], v[28:31]
	v_mfma_f32_16x16x32_bf16 v[24:27], v[52:55], v[160:163], v[24:27]
	v_mfma_f32_16x16x32_bf16 v[12:15], v[40:43], v[168:171], v[12:15]
	v_mfma_f32_16x16x32_bf16 v[8:11], v[52:55], v[168:171], v[8:11]
	v_mfma_f32_16x16x32_bf16 v[76:79], v[44:47], v[148:151], v[76:79]
	v_mfma_f32_16x16x32_bf16 v[72:75], v[60:63], v[148:151], v[72:75]
	v_mfma_f32_16x16x32_bf16 v[56:59], v[44:47], v[156:159], v[56:59]
	v_mfma_f32_16x16x32_bf16 v[48:51], v[60:63], v[156:159], v[48:51]
	v_mfma_f32_16x16x32_bf16 v[28:31], v[44:47], v[164:167], v[28:31]
	v_mfma_f32_16x16x32_bf16 v[24:27], v[60:63], v[164:167], v[24:27]
	v_mfma_f32_16x16x32_bf16 v[12:15], v[44:47], v[172:175], v[12:15]
	v_mfma_f32_16x16x32_bf16 v[8:11], v[60:63], v[172:175], v[8:11]
	s_barrier
	s_add_u32 s88, s28, 0x80000
	s_addc_u32 s89, s29, 0
	s_add_i32 s3, s80, s69
	s_mov_b32 m0, s3
	v_lshl_add_u64 v[40:41], s[88:89], 0, v[184:185]
	global_load_lds_dwordx4 v[40:41], off
	s_add_i32 m0, s3, 0x2000
	v_lshl_add_u64 v[40:41], s[88:89], 0, v[188:189]
	global_load_lds_dwordx4 v[40:41], off
	s_waitcnt vmcnt(6)
	s_barrier
	v_mfma_f32_16x16x32_bf16 v[36:39], v[198:201], v[152:155], v[36:39]
	v_mfma_f32_16x16x32_bf16 v[32:35], v[206:209], v[152:155], v[32:35]
	v_mfma_f32_16x16x32_bf16 v[20:23], v[198:201], v[160:163], v[20:23]
	v_mfma_f32_16x16x32_bf16 v[16:19], v[206:209], v[160:163], v[16:19]
	v_mfma_f32_16x16x32_bf16 v[4:7], v[198:201], v[168:171], v[4:7]
	v_mfma_f32_16x16x32_bf16 v[0:3], v[206:209], v[168:171], v[0:3]
	v_mfma_f32_16x16x32_bf16 v[40:43], v[198:201], v[144:147], v[68:71]
	v_mfma_f32_16x16x32_bf16 v[44:47], v[206:209], v[144:147], v[64:67]
	v_mfma_f32_16x16x32_bf16 v[36:39], v[202:205], v[156:159], v[36:39]
	v_mfma_f32_16x16x32_bf16 v[32:35], v[232:235], v[156:159], v[32:35]
	v_mfma_f32_16x16x32_bf16 v[20:23], v[202:205], v[164:167], v[20:23]
	v_mfma_f32_16x16x32_bf16 v[16:19], v[232:235], v[164:167], v[16:19]
	v_mfma_f32_16x16x32_bf16 v[4:7], v[202:205], v[172:175], v[4:7]
	v_mfma_f32_16x16x32_bf16 v[0:3], v[232:235], v[172:175], v[0:3]
	v_mfma_f32_16x16x32_bf16 v[40:43], v[202:205], v[148:151], v[40:43]
	v_mfma_f32_16x16x32_bf16 v[44:47], v[232:235], v[148:151], v[44:47]
	s_add_i32 s3, 0, 0x18000
	v_add_u32_e32 v68, s3, v226
	s_barrier
	ds_read_b128 v[52:55], v68
	ds_read_b128 v[60:63], v68 offset:1024
	ds_read_b128 v[64:67], v68 offset:2048
	ds_read_b128 v[68:71], v68 offset:3072
	s_add_u32 s34, s34, 0x80000
	s_addc_u32 s35, s35, 0
	s_mov_b32 m0, s67
	v_lshl_add_u64 v[198:199], s[34:35], 0, v[182:183]
	ds_read_b128 v[144:147], v229 offset:32768
	ds_read_b128 v[148:151], v229 offset:33792
	ds_read_b128 v[152:155], v229 offset:34816
	ds_read_b128 v[156:159], v229 offset:35840
	ds_read_b128 v[160:163], v229 offset:36864
	ds_read_b128 v[164:167], v229 offset:37888
	ds_read_b128 v[168:171], v229 offset:38912
	ds_read_b128 v[172:175], v229 offset:39936
	global_load_lds_dwordx4 v[198:199], off
	s_mov_b32 m0, s70
	v_lshl_add_u64 v[198:199], s[34:35], 0, v[186:187]
	global_load_lds_dwordx4 v[198:199], off
	s_waitcnt lgkmcnt(8)
	s_barrier
	s_waitcnt lgkmcnt(0)
	v_mfma_f32_16x16x32_bf16 v[140:143], v[52:55], v[144:147], v[140:143]
	v_mfma_f32_16x16x32_bf16 v[136:139], v[64:67], v[144:147], v[136:139]
	v_mfma_f32_16x16x32_bf16 v[124:127], v[52:55], v[152:155], v[124:127]
	v_mfma_f32_16x16x32_bf16 v[120:123], v[64:67], v[152:155], v[120:123]
	v_mfma_f32_16x16x32_bf16 v[108:111], v[52:55], v[160:163], v[108:111]
	v_mfma_f32_16x16x32_bf16 v[104:107], v[64:67], v[160:163], v[104:107]
	v_mfma_f32_16x16x32_bf16 v[92:95], v[52:55], v[168:171], v[92:95]
	v_mfma_f32_16x16x32_bf16 v[88:91], v[64:67], v[168:171], v[88:91]
	v_mfma_f32_16x16x32_bf16 v[140:143], v[60:63], v[148:151], v[140:143]
	v_mfma_f32_16x16x32_bf16 v[136:139], v[68:71], v[148:151], v[136:139]
	v_mfma_f32_16x16x32_bf16 v[124:127], v[60:63], v[156:159], v[124:127]
	v_mfma_f32_16x16x32_bf16 v[120:123], v[68:71], v[156:159], v[120:123]
	v_mfma_f32_16x16x32_bf16 v[108:111], v[60:63], v[164:167], v[108:111]
	v_mfma_f32_16x16x32_bf16 v[104:107], v[68:71], v[164:167], v[104:107]
	v_mfma_f32_16x16x32_bf16 v[92:95], v[60:63], v[172:175], v[92:95]
	v_mfma_f32_16x16x32_bf16 v[88:91], v[68:71], v[172:175], v[88:91]
	s_barrier
	s_add_i32 s34, 0, 0x1c000
	s_add_i32 s3, s3, s69
	v_add_u32_e32 v231, s34, v226
	v_lshl_add_u64 v[236:237], v[236:237], 0, s[22:23]
	s_mov_b32 m0, s3
	ds_read_b128 v[198:201], v231
	ds_read_b128 v[202:205], v231 offset:1024
	ds_read_b128 v[206:209], v231 offset:2048
	ds_read_b128 v[232:235], v231 offset:3072
	global_load_lds_dwordx4 v[236:237], off
	s_add_i32 m0, s3, 0x2000
	v_lshl_add_u64 v[236:237], v[238:239], 0, s[22:23]
	global_load_lds_dwordx4 v[236:237], off
	s_barrier
	s_waitcnt lgkmcnt(0)
	v_mfma_f32_16x16x32_bf16 v[132:135], v[198:201], v[144:147], v[132:135]
	v_mfma_f32_16x16x32_bf16 v[128:131], v[206:209], v[144:147], v[128:131]
	v_mfma_f32_16x16x32_bf16 v[116:119], v[198:201], v[152:155], v[116:119]
	v_mfma_f32_16x16x32_bf16 v[112:115], v[206:209], v[152:155], v[112:115]
	v_mfma_f32_16x16x32_bf16 v[100:103], v[198:201], v[160:163], v[100:103]
	v_mfma_f32_16x16x32_bf16 v[96:99], v[206:209], v[160:163], v[96:99]
	v_mfma_f32_16x16x32_bf16 v[84:87], v[198:201], v[168:171], v[84:87]
	v_mfma_f32_16x16x32_bf16 v[80:83], v[206:209], v[168:171], v[80:83]
	v_mfma_f32_16x16x32_bf16 v[132:135], v[202:205], v[148:151], v[132:135]
	v_mfma_f32_16x16x32_bf16 v[128:131], v[232:235], v[148:151], v[128:131]
	v_mfma_f32_16x16x32_bf16 v[116:119], v[202:205], v[156:159], v[116:119]
	v_mfma_f32_16x16x32_bf16 v[112:115], v[232:235], v[156:159], v[112:115]
	v_mfma_f32_16x16x32_bf16 v[100:103], v[202:205], v[164:167], v[100:103]
	v_mfma_f32_16x16x32_bf16 v[96:99], v[232:235], v[164:167], v[96:99]
	v_mfma_f32_16x16x32_bf16 v[84:87], v[202:205], v[172:175], v[84:87]
	v_mfma_f32_16x16x32_bf16 v[80:83], v[232:235], v[172:175], v[80:83]
	s_mov_b32 m0, s71
	v_lshl_add_u64 v[236:237], v[240:241], 0, s[22:23]
	s_barrier
	ds_read_b128 v[144:147], v229 offset:49152
	ds_read_b128 v[148:151], v229 offset:50176
	ds_read_b128 v[152:155], v229 offset:51200
	ds_read_b128 v[156:159], v229 offset:52224
	ds_read_b128 v[160:163], v229 offset:53248
	ds_read_b128 v[164:167], v229 offset:54272
	ds_read_b128 v[168:171], v229 offset:55296
	ds_read_b128 v[172:175], v229 offset:56320
	global_load_lds_dwordx4 v[236:237], off
	s_mov_b32 m0, s74
	v_lshl_add_u64 v[236:237], v[242:243], 0, s[22:23]
	global_load_lds_dwordx4 v[236:237], off
	s_barrier
	s_waitcnt lgkmcnt(0)
	v_mfma_f32_16x16x32_bf16 v[76:79], v[52:55], v[144:147], v[76:79]
	v_mfma_f32_16x16x32_bf16 v[72:75], v[64:67], v[144:147], v[72:75]
	v_mfma_f32_16x16x32_bf16 v[56:59], v[52:55], v[152:155], v[56:59]
	v_mfma_f32_16x16x32_bf16 v[48:51], v[64:67], v[152:155], v[48:51]
	v_mfma_f32_16x16x32_bf16 v[28:31], v[52:55], v[160:163], v[28:31]
	v_mfma_f32_16x16x32_bf16 v[24:27], v[64:67], v[160:163], v[24:27]
	v_mfma_f32_16x16x32_bf16 v[12:15], v[52:55], v[168:171], v[12:15]
	v_mfma_f32_16x16x32_bf16 v[8:11], v[64:67], v[168:171], v[8:11]
	v_mfma_f32_16x16x32_bf16 v[76:79], v[60:63], v[148:151], v[76:79]
	v_mfma_f32_16x16x32_bf16 v[72:75], v[68:71], v[148:151], v[72:75]
	v_mfma_f32_16x16x32_bf16 v[56:59], v[60:63], v[156:159], v[56:59]
	v_mfma_f32_16x16x32_bf16 v[48:51], v[68:71], v[156:159], v[48:51]
	v_mfma_f32_16x16x32_bf16 v[28:31], v[60:63], v[164:167], v[28:31]
	v_mfma_f32_16x16x32_bf16 v[24:27], v[68:71], v[164:167], v[24:27]
	v_mfma_f32_16x16x32_bf16 v[12:15], v[60:63], v[172:175], v[12:15]
	v_mfma_f32_16x16x32_bf16 v[8:11], v[68:71], v[172:175], v[8:11]
	s_barrier
	s_add_u32 s28, s28, 0x80080
	s_addc_u32 s29, s29, 0
	s_add_i32 s3, s34, s69
	s_mov_b32 m0, s3
	v_lshl_add_u64 v[52:53], s[28:29], 0, v[184:185]
	global_load_lds_dwordx4 v[52:53], off
	s_add_i32 m0, s3, 0x2000
	v_lshl_add_u64 v[52:53], s[28:29], 0, v[188:189]
	global_load_lds_dwordx4 v[52:53], off
	s_waitcnt vmcnt(6)
	s_barrier
	v_mfma_f32_16x16x32_bf16 v[40:43], v[198:201], v[144:147], v[40:43]
	v_mfma_f32_16x16x32_bf16 v[68:71], v[202:205], v[148:151], v[40:43]
	v_mfma_f32_16x16x32_bf16 v[40:43], v[206:209], v[144:147], v[44:47]
	v_mfma_f32_16x16x32_bf16 v[36:39], v[198:201], v[152:155], v[36:39]
	v_mfma_f32_16x16x32_bf16 v[32:35], v[206:209], v[152:155], v[32:35]
	v_mfma_f32_16x16x32_bf16 v[20:23], v[198:201], v[160:163], v[20:23]
	v_mfma_f32_16x16x32_bf16 v[16:19], v[206:209], v[160:163], v[16:19]
	v_mfma_f32_16x16x32_bf16 v[4:7], v[198:201], v[168:171], v[4:7]
	v_mfma_f32_16x16x32_bf16 v[0:3], v[206:209], v[168:171], v[0:3]
	v_mfma_f32_16x16x32_bf16 v[64:67], v[232:235], v[148:151], v[40:43]
	v_mfma_f32_16x16x32_bf16 v[36:39], v[202:205], v[156:159], v[36:39]
	v_mfma_f32_16x16x32_bf16 v[32:35], v[232:235], v[156:159], v[32:35]
	v_mfma_f32_16x16x32_bf16 v[20:23], v[202:205], v[164:167], v[20:23]
	v_mfma_f32_16x16x32_bf16 v[16:19], v[232:235], v[164:167], v[16:19]
	v_mfma_f32_16x16x32_bf16 v[4:7], v[202:205], v[172:175], v[4:7]
	v_mfma_f32_16x16x32_bf16 v[0:3], v[232:235], v[172:175], v[0:3]
	s_add_i32 s3, s86, 2
	s_add_u32 s10, s10, 0x100
	s_addc_u32 s11, s11, 0
	s_add_u32 s51, s51, 0x100
	s_addc_u32 s85, s85, 0
	s_cmp_ge_u32 s86, s84
	s_mov_b32 s86, s3
	s_barrier
	s_cbranch_scc0 .LBB0_558

.LBB0_639:
	s_mov_b64 s[34:35], s[8:9]
	s_add_u32 s83, s34, 0x100
	s_addc_u32 s84, s35, 0
	v_add_co_u32_e64 v56, s[26:27], s80, 1
	s_and_b64 s[8:9], s[26:27], exec
	s_cselect_b32 s10, s4, s69
	s_cselect_b32 s82, s66, 0
	s_cmp_gt_i32 s80, 0
	s_cselect_b64 s[20:21], -1, 0
	s_ashr_i32 s11, s10, 31
	s_lshl_b64 s[8:9], s[10:11], 21
	s_add_u32 s3, s56, s8
	s_addc_u32 s8, s57, s9
	s_lshl_b32 s9, s82, 1
	s_add_u32 s24, s3, s9
	s_addc_u32 s25, s8, 0
	s_add_u32 s8, s42, s9
	s_addc_u32 s9, s43, 0
	s_cmp_lt_i32 s80, 1
	s_cselect_b64 s[28:29], -1, 0
	s_and_b64 s[36:37], s[28:29], exec
	s_cselect_b32 s11, s25, s23
	s_cselect_b32 s85, s24, s22
	s_cselect_b32 s86, s9, s35
	s_cselect_b32 s87, s8, s34
	s_lshl_b32 s3, s49, 7
	s_addk_i32 s3, 0xfc00
	v_readfirstlane_b32 s81, v56
	v_lshl_add_u64 v[58:59], s[22:23], 0, v[142:143]
	v_lshl_add_u64 v[146:147], s[22:23], 0, v[144:145]
	s_add_u32 s88, s3, 0x300
	s_mov_b64 s[34:35], 0
	s_mov_b32 s89, 0
	s_add_i32 s89, s89, 2
	v_add_u32_e32 v56, s71, v139
	s_add_u32 s3, s22, s34
	ds_read_b128 v[150:153], v56
	ds_read_b128 v[154:157], v56 offset:1024
	ds_read_b128 v[158:161], v56 offset:2048
	ds_read_b128 v[162:165], v56 offset:3072
	s_addc_u32 s36, s23, s35
	s_add_u32 s3, s3, 0x100
	s_addc_u32 s36, s36, 0
	s_add_u32 s90, s83, s34
	s_addc_u32 s37, s84, s35
	s_cmp_eq_u32 s88, s34
	s_cselect_b32 s39, s11, s36
	s_cselect_b32 s38, s85, s3
	s_cselect_b32 s37, s86, s37
	s_cselect_b32 s36, s87, s90
	s_mov_b32 m0, s73
	v_lshl_add_u64 v[174:175], v[58:59], 0, s[34:35]
	ds_read_b128 v[166:169], v133
	ds_read_b128 v[170:173], v133 offset:1024
	ds_read_b128 v[182:185], v133 offset:2048
	ds_read_b128 v[186:189], v133 offset:3072
	ds_read_b128 v[190:193], v133 offset:4096
	ds_read_b128 v[194:197], v133 offset:5120
	ds_read_b128 v[198:201], v133 offset:6144
	ds_read_b128 v[202:205], v133 offset:7168
	global_load_lds_dwordx4 v[174:175], off
	s_mov_b32 m0, s74
	v_lshl_add_u64 v[174:175], v[146:147], 0, s[34:35]
	global_load_lds_dwordx4 v[174:175], off
	s_waitcnt lgkmcnt(8)
	s_barrier
	s_waitcnt lgkmcnt(0)
	v_mfma_f32_16x16x32_bf16 v[128:131], v[150:153], v[166:169], 0
	v_mfma_f32_16x16x32_bf16 v[124:127], v[158:161], v[166:169], 0
	v_mfma_f32_16x16x32_bf16 v[112:115], v[150:153], v[182:185], 0
	v_mfma_f32_16x16x32_bf16 v[108:111], v[158:161], v[182:185], 0
	v_mfma_f32_16x16x32_bf16 v[96:99], v[150:153], v[190:193], 0
	v_mfma_f32_16x16x32_bf16 v[92:95], v[158:161], v[190:193], 0
	v_mfma_f32_16x16x32_bf16 v[80:83], v[150:153], v[198:201], 0
	v_mfma_f32_16x16x32_bf16 v[76:79], v[158:161], v[198:201], 0
	v_mfma_f32_16x16x32_bf16 v[128:131], v[154:157], v[170:173], v[128:131]
	v_mfma_f32_16x16x32_bf16 v[124:127], v[162:165], v[170:173], v[124:127]
	v_mfma_f32_16x16x32_bf16 v[112:115], v[154:157], v[186:189], v[112:115]
	v_mfma_f32_16x16x32_bf16 v[108:111], v[162:165], v[186:189], v[108:111]
	v_mfma_f32_16x16x32_bf16 v[96:99], v[154:157], v[194:197], v[96:99]
	v_mfma_f32_16x16x32_bf16 v[92:95], v[162:165], v[194:197], v[92:95]
	v_mfma_f32_16x16x32_bf16 v[80:83], v[154:157], v[202:205], v[80:83]
	v_mfma_f32_16x16x32_bf16 v[76:79], v[162:165], v[202:205], v[76:79]
	s_barrier
	s_mov_b32 m0, s75
	v_add_u32_e32 v56, s72, v139
	v_lshl_add_u64 v[174:175], s[36:37], 0, v[134:135]
	ds_read_b128 v[206:209], v56
	ds_read_b128 v[214:217], v56 offset:1024
	ds_read_b128 v[218:221], v56 offset:2048
	ds_read_b128 v[222:225], v56 offset:3072
	global_load_lds_dwordx4 v[174:175], off
	s_mov_b32 m0, s76
	v_lshl_add_u64 v[226:227], s[36:37], 0, v[136:137]
	global_load_lds_dwordx4 v[226:227], off
	s_barrier
	s_waitcnt lgkmcnt(0)
	v_mfma_f32_16x16x32_bf16 v[120:123], v[206:209], v[166:169], 0
	v_mfma_f32_16x16x32_bf16 v[116:119], v[218:221], v[166:169], 0
	v_mfma_f32_16x16x32_bf16 v[104:107], v[206:209], v[182:185], 0
	v_mfma_f32_16x16x32_bf16 v[100:103], v[218:221], v[182:185], 0
	v_mfma_f32_16x16x32_bf16 v[88:91], v[206:209], v[190:193], 0
	v_mfma_f32_16x16x32_bf16 v[84:87], v[218:221], v[190:193], 0
	v_mfma_f32_16x16x32_bf16 v[72:75], v[206:209], v[198:201], 0
	v_mfma_f32_16x16x32_bf16 v[68:71], v[218:221], v[198:201], 0
	v_mfma_f32_16x16x32_bf16 v[120:123], v[214:217], v[170:173], v[120:123]
	v_mfma_f32_16x16x32_bf16 v[116:119], v[222:225], v[170:173], v[116:119]
	v_mfma_f32_16x16x32_bf16 v[104:107], v[214:217], v[186:189], v[104:107]
	v_mfma_f32_16x16x32_bf16 v[100:103], v[222:225], v[186:189], v[100:103]
	v_mfma_f32_16x16x32_bf16 v[88:91], v[214:217], v[194:197], v[88:91]
	v_mfma_f32_16x16x32_bf16 v[84:87], v[222:225], v[194:197], v[84:87]
	v_mfma_f32_16x16x32_bf16 v[72:75], v[214:217], v[202:205], v[72:75]
	v_mfma_f32_16x16x32_bf16 v[68:71], v[222:225], v[202:205], v[68:71]
	s_mov_b32 m0, s44
	v_lshl_add_u64 v[228:229], s[38:39], 0, v[134:135]
	s_barrier
	ds_read_b128 v[166:169], v133 offset:16384
	ds_read_b128 v[170:173], v133 offset:17408
	ds_read_b128 v[182:185], v133 offset:18432
	ds_read_b128 v[186:189], v133 offset:19456
	ds_read_b128 v[190:193], v133 offset:20480
	ds_read_b128 v[194:197], v133 offset:21504
	ds_read_b128 v[198:201], v133 offset:22528
	ds_read_b128 v[202:205], v133 offset:23552
	global_load_lds_dwordx4 v[228:229], off
	s_mov_b32 m0, s45
	v_lshl_add_u64 v[230:231], s[38:39], 0, v[136:137]
	global_load_lds_dwordx4 v[230:231], off
	s_barrier
	s_waitcnt lgkmcnt(0)
	v_mfma_f32_16x16x32_bf16 v[64:67], v[150:153], v[166:169], 0
	v_mfma_f32_16x16x32_bf16 v[60:63], v[158:161], v[166:169], 0
	v_mfma_f32_16x16x32_bf16 v[44:47], v[150:153], v[182:185], 0
	v_mfma_f32_16x16x32_bf16 v[40:43], v[158:161], v[182:185], 0
	v_mfma_f32_16x16x32_bf16 v[28:31], v[150:153], v[190:193], 0
	v_mfma_f32_16x16x32_bf16 v[24:27], v[158:161], v[190:193], 0
	v_mfma_f32_16x16x32_bf16 v[12:15], v[150:153], v[198:201], 0
	v_mfma_f32_16x16x32_bf16 v[8:11], v[158:161], v[198:201], 0
	v_mfma_f32_16x16x32_bf16 v[64:67], v[154:157], v[170:173], v[64:67]
	v_mfma_f32_16x16x32_bf16 v[60:63], v[162:165], v[170:173], v[60:63]
	v_mfma_f32_16x16x32_bf16 v[44:47], v[154:157], v[186:189], v[44:47]
	v_mfma_f32_16x16x32_bf16 v[40:43], v[162:165], v[186:189], v[40:43]
	v_mfma_f32_16x16x32_bf16 v[28:31], v[154:157], v[194:197], v[28:31]
	v_mfma_f32_16x16x32_bf16 v[24:27], v[162:165], v[194:197], v[24:27]
	v_mfma_f32_16x16x32_bf16 v[12:15], v[154:157], v[202:205], v[12:15]
	v_mfma_f32_16x16x32_bf16 v[8:11], v[162:165], v[202:205], v[8:11]
	s_barrier
	s_add_u32 s90, s36, 0x100000
	s_addc_u32 s91, s37, 0
	s_mov_b32 m0, s77
	v_lshl_add_u64 v[150:151], s[90:91], 0, v[134:135]
	global_load_lds_dwordx4 v[150:151], off
	s_mov_b32 m0, s78
	v_lshl_add_u64 v[150:151], s[90:91], 0, v[136:137]
	global_load_lds_dwordx4 v[150:151], off
	s_waitcnt vmcnt(6)
	s_barrier
	v_mfma_f32_16x16x32_bf16 v[52:55], v[206:209], v[166:169], 0
	v_mfma_f32_16x16x32_bf16 v[48:51], v[218:221], v[166:169], 0
	v_mfma_f32_16x16x32_bf16 v[36:39], v[206:209], v[182:185], 0
	v_mfma_f32_16x16x32_bf16 v[32:35], v[218:221], v[182:185], 0
	v_mfma_f32_16x16x32_bf16 v[20:23], v[206:209], v[190:193], 0
	v_mfma_f32_16x16x32_bf16 v[16:19], v[218:221], v[190:193], 0
	v_mfma_f32_16x16x32_bf16 v[4:7], v[206:209], v[198:201], 0
	v_mfma_f32_16x16x32_bf16 v[0:3], v[218:221], v[198:201], 0
	v_mfma_f32_16x16x32_bf16 v[52:55], v[214:217], v[170:173], v[52:55]
	v_mfma_f32_16x16x32_bf16 v[48:51], v[222:225], v[170:173], v[48:51]
	v_mfma_f32_16x16x32_bf16 v[36:39], v[214:217], v[186:189], v[36:39]
	v_mfma_f32_16x16x32_bf16 v[32:35], v[222:225], v[186:189], v[32:35]
	v_mfma_f32_16x16x32_bf16 v[20:23], v[214:217], v[194:197], v[20:23]
	v_mfma_f32_16x16x32_bf16 v[16:19], v[222:225], v[194:197], v[16:19]
	v_mfma_f32_16x16x32_bf16 v[4:7], v[214:217], v[202:205], v[4:7]
	v_mfma_f32_16x16x32_bf16 v[0:3], v[222:225], v[202:205], v[0:3]
	v_add_u32_e32 v56, s79, v139
	s_barrier
	ds_read_b128 v[150:153], v56
	ds_read_b128 v[154:157], v56 offset:1024
	ds_read_b128 v[158:161], v56 offset:2048
	ds_read_b128 v[162:165], v56 offset:3072
	s_add_u32 s38, s38, 0x100000
	s_addc_u32 s39, s39, 0
	s_mov_b32 m0, s46
	v_lshl_add_u64 v[206:207], s[38:39], 0, v[134:135]
	ds_read_b128 v[166:169], v133 offset:32768
	ds_read_b128 v[170:173], v133 offset:33792
	ds_read_b128 v[182:185], v133 offset:34816
	ds_read_b128 v[186:189], v133 offset:35840
	ds_read_b128 v[190:193], v133 offset:36864
	ds_read_b128 v[194:197], v133 offset:37888
	ds_read_b128 v[198:201], v133 offset:38912
	ds_read_b128 v[202:205], v133 offset:39936
	global_load_lds_dwordx4 v[206:207], off
	s_mov_b32 m0, s47
	v_lshl_add_u64 v[206:207], s[38:39], 0, v[136:137]
	global_load_lds_dwordx4 v[206:207], off
	s_waitcnt lgkmcnt(8)
	s_barrier
	s_waitcnt lgkmcnt(0)
	v_mfma_f32_16x16x32_bf16 v[128:131], v[150:153], v[166:169], v[128:131]
	v_mfma_f32_16x16x32_bf16 v[124:127], v[158:161], v[166:169], v[124:127]
	v_mfma_f32_16x16x32_bf16 v[112:115], v[150:153], v[182:185], v[112:115]
	v_mfma_f32_16x16x32_bf16 v[108:111], v[158:161], v[182:185], v[108:111]
	v_mfma_f32_16x16x32_bf16 v[96:99], v[150:153], v[190:193], v[96:99]
	v_mfma_f32_16x16x32_bf16 v[92:95], v[158:161], v[190:193], v[92:95]
	v_mfma_f32_16x16x32_bf16 v[80:83], v[150:153], v[198:201], v[80:83]
	v_mfma_f32_16x16x32_bf16 v[76:79], v[158:161], v[198:201], v[76:79]
	v_mfma_f32_16x16x32_bf16 v[128:131], v[154:157], v[170:173], v[128:131]
	v_mfma_f32_16x16x32_bf16 v[124:127], v[162:165], v[170:173], v[124:127]
	v_mfma_f32_16x16x32_bf16 v[112:115], v[154:157], v[186:189], v[112:115]
	v_mfma_f32_16x16x32_bf16 v[108:111], v[162:165], v[186:189], v[108:111]
	v_mfma_f32_16x16x32_bf16 v[96:99], v[154:157], v[194:197], v[96:99]
	v_mfma_f32_16x16x32_bf16 v[92:95], v[162:165], v[194:197], v[92:95]
	v_mfma_f32_16x16x32_bf16 v[80:83], v[154:157], v[202:205], v[80:83]
	v_mfma_f32_16x16x32_bf16 v[76:79], v[162:165], v[202:205], v[76:79]
	s_barrier
	s_add_i32 s3, 0, 0x1c000
	s_add_i32 s38, s79, s41
	v_add_u32_e32 v56, s3, v139
	v_lshl_add_u64 v[174:175], v[174:175], 0, s[16:17]
	s_mov_b32 m0, s38
	ds_read_b128 v[206:209], v56
	ds_read_b128 v[214:217], v56 offset:1024
	ds_read_b128 v[218:221], v56 offset:2048
	ds_read_b128 v[222:225], v56 offset:3072
	global_load_lds_dwordx4 v[174:175], off
	s_add_i32 m0, s38, 0x2000
	v_lshl_add_u64 v[174:175], v[226:227], 0, s[16:17]
	global_load_lds_dwordx4 v[174:175], off
	s_barrier
	s_waitcnt lgkmcnt(0)
	v_mfma_f32_16x16x32_bf16 v[120:123], v[206:209], v[166:169], v[120:123]
	v_mfma_f32_16x16x32_bf16 v[116:119], v[218:221], v[166:169], v[116:119]
	v_mfma_f32_16x16x32_bf16 v[104:107], v[206:209], v[182:185], v[104:107]
	v_mfma_f32_16x16x32_bf16 v[100:103], v[218:221], v[182:185], v[100:103]
	v_mfma_f32_16x16x32_bf16 v[88:91], v[206:209], v[190:193], v[88:91]
	v_mfma_f32_16x16x32_bf16 v[84:87], v[218:221], v[190:193], v[84:87]
	v_mfma_f32_16x16x32_bf16 v[72:75], v[206:209], v[198:201], v[72:75]
	v_mfma_f32_16x16x32_bf16 v[68:71], v[218:221], v[198:201], v[68:71]
	v_mfma_f32_16x16x32_bf16 v[120:123], v[214:217], v[170:173], v[120:123]
	v_mfma_f32_16x16x32_bf16 v[116:119], v[222:225], v[170:173], v[116:119]
	v_mfma_f32_16x16x32_bf16 v[104:107], v[214:217], v[186:189], v[104:107]
	v_mfma_f32_16x16x32_bf16 v[100:103], v[222:225], v[186:189], v[100:103]
	v_mfma_f32_16x16x32_bf16 v[88:91], v[214:217], v[194:197], v[88:91]
	v_mfma_f32_16x16x32_bf16 v[84:87], v[222:225], v[194:197], v[84:87]
	v_mfma_f32_16x16x32_bf16 v[72:75], v[214:217], v[202:205], v[72:75]
	v_mfma_f32_16x16x32_bf16 v[68:71], v[222:225], v[202:205], v[68:71]
	s_mov_b32 m0, s67
	v_lshl_add_u64 v[174:175], v[228:229], 0, s[16:17]
	s_barrier
	ds_read_b128 v[166:169], v133 offset:49152
	ds_read_b128 v[170:173], v133 offset:50176
	ds_read_b128 v[182:185], v133 offset:51200
	ds_read_b128 v[186:189], v133 offset:52224
	ds_read_b128 v[190:193], v133 offset:53248
	ds_read_b128 v[194:197], v133 offset:54272
	ds_read_b128 v[198:201], v133 offset:55296
	ds_read_b128 v[202:205], v133 offset:56320
	global_load_lds_dwordx4 v[174:175], off
	s_mov_b32 m0, s68
	v_lshl_add_u64 v[174:175], v[230:231], 0, s[16:17]
	global_load_lds_dwordx4 v[174:175], off
	s_barrier
	s_waitcnt lgkmcnt(0)
	v_mfma_f32_16x16x32_bf16 v[64:67], v[150:153], v[166:169], v[64:67]
	v_mfma_f32_16x16x32_bf16 v[60:63], v[158:161], v[166:169], v[60:63]
	v_mfma_f32_16x16x32_bf16 v[44:47], v[150:153], v[182:185], v[44:47]
	v_mfma_f32_16x16x32_bf16 v[40:43], v[158:161], v[182:185], v[40:43]
	v_mfma_f32_16x16x32_bf16 v[28:31], v[150:153], v[190:193], v[28:31]
	v_mfma_f32_16x16x32_bf16 v[24:27], v[158:161], v[190:193], v[24:27]
	v_mfma_f32_16x16x32_bf16 v[12:15], v[150:153], v[198:201], v[12:15]
	v_mfma_f32_16x16x32_bf16 v[8:11], v[158:161], v[198:201], v[8:11]
	v_mfma_f32_16x16x32_bf16 v[64:67], v[154:157], v[170:173], v[64:67]
	v_mfma_f32_16x16x32_bf16 v[60:63], v[162:165], v[170:173], v[60:63]
	v_mfma_f32_16x16x32_bf16 v[44:47], v[154:157], v[186:189], v[44:47]
	v_mfma_f32_16x16x32_bf16 v[40:43], v[162:165], v[186:189], v[40:43]
	v_mfma_f32_16x16x32_bf16 v[28:31], v[154:157], v[194:197], v[28:31]
	v_mfma_f32_16x16x32_bf16 v[24:27], v[162:165], v[194:197], v[24:27]
	v_mfma_f32_16x16x32_bf16 v[12:15], v[154:157], v[202:205], v[12:15]
	v_mfma_f32_16x16x32_bf16 v[8:11], v[162:165], v[202:205], v[8:11]
	s_barrier
	s_add_u32 s36, s36, 0x100080
	s_addc_u32 s37, s37, 0
	s_add_i32 s3, s3, s41
	s_mov_b32 m0, s3
	v_lshl_add_u64 v[150:151], s[36:37], 0, v[134:135]
	global_load_lds_dwordx4 v[150:151], off
	s_add_i32 m0, s3, 0x2000
	v_lshl_add_u64 v[150:151], s[36:37], 0, v[136:137]
	global_load_lds_dwordx4 v[150:151], off
	s_waitcnt vmcnt(6)
	s_barrier
	v_mfma_f32_16x16x32_bf16 v[52:55], v[206:209], v[166:169], v[52:55]
	v_mfma_f32_16x16x32_bf16 v[48:51], v[218:221], v[166:169], v[48:51]
	v_mfma_f32_16x16x32_bf16 v[36:39], v[206:209], v[182:185], v[36:39]
	v_mfma_f32_16x16x32_bf16 v[32:35], v[218:221], v[182:185], v[32:35]
	v_mfma_f32_16x16x32_bf16 v[20:23], v[206:209], v[190:193], v[20:23]
	v_mfma_f32_16x16x32_bf16 v[16:19], v[218:221], v[190:193], v[16:19]
	v_mfma_f32_16x16x32_bf16 v[4:7], v[206:209], v[198:201], v[4:7]
	v_mfma_f32_16x16x32_bf16 v[0:3], v[218:221], v[198:201], v[0:3]
	v_mfma_f32_16x16x32_bf16 v[52:55], v[214:217], v[170:173], v[52:55]
	v_mfma_f32_16x16x32_bf16 v[48:51], v[222:225], v[170:173], v[48:51]
	v_mfma_f32_16x16x32_bf16 v[36:39], v[214:217], v[186:189], v[36:39]
	v_mfma_f32_16x16x32_bf16 v[32:35], v[222:225], v[186:189], v[32:35]
	v_mfma_f32_16x16x32_bf16 v[20:23], v[214:217], v[194:197], v[20:23]
	v_mfma_f32_16x16x32_bf16 v[16:19], v[222:225], v[194:197], v[16:19]
	v_mfma_f32_16x16x32_bf16 v[4:7], v[214:217], v[202:205], v[4:7]
	v_mfma_f32_16x16x32_bf16 v[0:3], v[222:225], v[202:205], v[0:3]
	s_add_u32 s34, s34, 0x100
	s_addc_u32 s35, s35, 0
	s_cmp_ge_u32 s89, s49
	s_barrier
	s_cbranch_scc1 .Lpeel_done_out
.LBB0_640:
	s_add_i32 s89, s89, 2
	v_add_u32_e32 v56, s71, v139
	s_add_u32 s3, s22, s34
	ds_read_b128 v[150:153], v56
	ds_read_b128 v[154:157], v56 offset:1024
	ds_read_b128 v[158:161], v56 offset:2048
	ds_read_b128 v[162:165], v56 offset:3072
	s_addc_u32 s36, s23, s35
	s_add_u32 s3, s3, 0x100
	s_addc_u32 s36, s36, 0
	s_add_u32 s90, s83, s34
	s_addc_u32 s37, s84, s35
	s_cmp_eq_u32 s88, s34
	s_cselect_b32 s39, s11, s36
	s_cselect_b32 s38, s85, s3
	s_cselect_b32 s37, s86, s37
	s_cselect_b32 s36, s87, s90
	s_mov_b32 m0, s73
	v_lshl_add_u64 v[174:175], v[58:59], 0, s[34:35]
	ds_read_b128 v[166:169], v133
	ds_read_b128 v[170:173], v133 offset:1024
	ds_read_b128 v[182:185], v133 offset:2048
	ds_read_b128 v[186:189], v133 offset:3072
	ds_read_b128 v[190:193], v133 offset:4096
	ds_read_b128 v[194:197], v133 offset:5120
	ds_read_b128 v[198:201], v133 offset:6144
	ds_read_b128 v[202:205], v133 offset:7168
	global_load_lds_dwordx4 v[174:175], off
	s_mov_b32 m0, s74
	v_lshl_add_u64 v[174:175], v[146:147], 0, s[34:35]
	global_load_lds_dwordx4 v[174:175], off
	s_waitcnt lgkmcnt(8)
	s_barrier
	s_waitcnt lgkmcnt(0)
	v_mfma_f32_16x16x32_bf16 v[128:131], v[150:153], v[166:169], v[128:131]
	v_mfma_f32_16x16x32_bf16 v[124:127], v[158:161], v[166:169], v[124:127]
	v_mfma_f32_16x16x32_bf16 v[112:115], v[150:153], v[182:185], v[112:115]
	v_mfma_f32_16x16x32_bf16 v[108:111], v[158:161], v[182:185], v[108:111]
	v_mfma_f32_16x16x32_bf16 v[96:99], v[150:153], v[190:193], v[96:99]
	v_mfma_f32_16x16x32_bf16 v[92:95], v[158:161], v[190:193], v[92:95]
	v_mfma_f32_16x16x32_bf16 v[80:83], v[150:153], v[198:201], v[80:83]
	v_mfma_f32_16x16x32_bf16 v[76:79], v[158:161], v[198:201], v[76:79]
	v_mfma_f32_16x16x32_bf16 v[128:131], v[154:157], v[170:173], v[128:131]
	v_mfma_f32_16x16x32_bf16 v[124:127], v[162:165], v[170:173], v[124:127]
	v_mfma_f32_16x16x32_bf16 v[112:115], v[154:157], v[186:189], v[112:115]
	v_mfma_f32_16x16x32_bf16 v[108:111], v[162:165], v[186:189], v[108:111]
	v_mfma_f32_16x16x32_bf16 v[96:99], v[154:157], v[194:197], v[96:99]
	v_mfma_f32_16x16x32_bf16 v[92:95], v[162:165], v[194:197], v[92:95]
	v_mfma_f32_16x16x32_bf16 v[80:83], v[154:157], v[202:205], v[80:83]
	v_mfma_f32_16x16x32_bf16 v[76:79], v[162:165], v[202:205], v[76:79]
	s_barrier
	s_mov_b32 m0, s75
	v_add_u32_e32 v56, s72, v139
	v_lshl_add_u64 v[174:175], s[36:37], 0, v[134:135]
	ds_read_b128 v[206:209], v56
	ds_read_b128 v[214:217], v56 offset:1024
	ds_read_b128 v[218:221], v56 offset:2048
	ds_read_b128 v[222:225], v56 offset:3072
	global_load_lds_dwordx4 v[174:175], off
	s_mov_b32 m0, s76
	v_lshl_add_u64 v[226:227], s[36:37], 0, v[136:137]
	global_load_lds_dwordx4 v[226:227], off
	s_barrier
	s_waitcnt lgkmcnt(0)
	v_mfma_f32_16x16x32_bf16 v[120:123], v[206:209], v[166:169], v[120:123]
	v_mfma_f32_16x16x32_bf16 v[116:119], v[218:221], v[166:169], v[116:119]
	v_mfma_f32_16x16x32_bf16 v[104:107], v[206:209], v[182:185], v[104:107]
	v_mfma_f32_16x16x32_bf16 v[100:103], v[218:221], v[182:185], v[100:103]
	v_mfma_f32_16x16x32_bf16 v[88:91], v[206:209], v[190:193], v[88:91]
	v_mfma_f32_16x16x32_bf16 v[84:87], v[218:221], v[190:193], v[84:87]
	v_mfma_f32_16x16x32_bf16 v[72:75], v[206:209], v[198:201], v[72:75]
	v_mfma_f32_16x16x32_bf16 v[68:71], v[218:221], v[198:201], v[68:71]
	v_mfma_f32_16x16x32_bf16 v[120:123], v[214:217], v[170:173], v[120:123]
	v_mfma_f32_16x16x32_bf16 v[116:119], v[222:225], v[170:173], v[116:119]
	v_mfma_f32_16x16x32_bf16 v[104:107], v[214:217], v[186:189], v[104:107]
	v_mfma_f32_16x16x32_bf16 v[100:103], v[222:225], v[186:189], v[100:103]
	v_mfma_f32_16x16x32_bf16 v[88:91], v[214:217], v[194:197], v[88:91]
	v_mfma_f32_16x16x32_bf16 v[84:87], v[222:225], v[194:197], v[84:87]
	v_mfma_f32_16x16x32_bf16 v[72:75], v[214:217], v[202:205], v[72:75]
	v_mfma_f32_16x16x32_bf16 v[68:71], v[222:225], v[202:205], v[68:71]
	s_mov_b32 m0, s44
	v_lshl_add_u64 v[228:229], s[38:39], 0, v[134:135]
	s_barrier
	ds_read_b128 v[166:169], v133 offset:16384
	ds_read_b128 v[170:173], v133 offset:17408
	ds_read_b128 v[182:185], v133 offset:18432
	ds_read_b128 v[186:189], v133 offset:19456
	ds_read_b128 v[190:193], v133 offset:20480
	ds_read_b128 v[194:197], v133 offset:21504
	ds_read_b128 v[198:201], v133 offset:22528
	ds_read_b128 v[202:205], v133 offset:23552
	global_load_lds_dwordx4 v[228:229], off
	s_mov_b32 m0, s45
	v_lshl_add_u64 v[230:231], s[38:39], 0, v[136:137]
	global_load_lds_dwordx4 v[230:231], off
	s_barrier
	s_waitcnt lgkmcnt(0)
	v_mfma_f32_16x16x32_bf16 v[64:67], v[150:153], v[166:169], v[64:67]
	v_mfma_f32_16x16x32_bf16 v[60:63], v[158:161], v[166:169], v[60:63]
	v_mfma_f32_16x16x32_bf16 v[44:47], v[150:153], v[182:185], v[44:47]
	v_mfma_f32_16x16x32_bf16 v[40:43], v[158:161], v[182:185], v[40:43]
	v_mfma_f32_16x16x32_bf16 v[28:31], v[150:153], v[190:193], v[28:31]
	v_mfma_f32_16x16x32_bf16 v[24:27], v[158:161], v[190:193], v[24:27]
	v_mfma_f32_16x16x32_bf16 v[12:15], v[150:153], v[198:201], v[12:15]
	v_mfma_f32_16x16x32_bf16 v[8:11], v[158:161], v[198:201], v[8:11]
	v_mfma_f32_16x16x32_bf16 v[64:67], v[154:157], v[170:173], v[64:67]
	v_mfma_f32_16x16x32_bf16 v[60:63], v[162:165], v[170:173], v[60:63]
	v_mfma_f32_16x16x32_bf16 v[44:47], v[154:157], v[186:189], v[44:47]
	v_mfma_f32_16x16x32_bf16 v[40:43], v[162:165], v[186:189], v[40:43]
	v_mfma_f32_16x16x32_bf16 v[28:31], v[154:157], v[194:197], v[28:31]
	v_mfma_f32_16x16x32_bf16 v[24:27], v[162:165], v[194:197], v[24:27]
	v_mfma_f32_16x16x32_bf16 v[12:15], v[154:157], v[202:205], v[12:15]
	v_mfma_f32_16x16x32_bf16 v[8:11], v[162:165], v[202:205], v[8:11]
	s_barrier
	s_add_u32 s90, s36, 0x100000
	s_addc_u32 s91, s37, 0
	s_mov_b32 m0, s77
	v_lshl_add_u64 v[150:151], s[90:91], 0, v[134:135]
	global_load_lds_dwordx4 v[150:151], off
	s_mov_b32 m0, s78
	v_lshl_add_u64 v[150:151], s[90:91], 0, v[136:137]
	global_load_lds_dwordx4 v[150:151], off
	s_waitcnt vmcnt(6)
	s_barrier
	v_mfma_f32_16x16x32_bf16 v[52:55], v[206:209], v[166:169], v[52:55]
	v_mfma_f32_16x16x32_bf16 v[48:51], v[218:221], v[166:169], v[48:51]
	v_mfma_f32_16x16x32_bf16 v[36:39], v[206:209], v[182:185], v[36:39]
	v_mfma_f32_16x16x32_bf16 v[32:35], v[218:221], v[182:185], v[32:35]
	v_mfma_f32_16x16x32_bf16 v[20:23], v[206:209], v[190:193], v[20:23]
	v_mfma_f32_16x16x32_bf16 v[16:19], v[218:221], v[190:193], v[16:19]
	v_mfma_f32_16x16x32_bf16 v[4:7], v[206:209], v[198:201], v[4:7]
	v_mfma_f32_16x16x32_bf16 v[0:3], v[218:221], v[198:201], v[0:3]
	v_mfma_f32_16x16x32_bf16 v[52:55], v[214:217], v[170:173], v[52:55]
	v_mfma_f32_16x16x32_bf16 v[48:51], v[222:225], v[170:173], v[48:51]
	v_mfma_f32_16x16x32_bf16 v[36:39], v[214:217], v[186:189], v[36:39]
	v_mfma_f32_16x16x32_bf16 v[32:35], v[222:225], v[186:189], v[32:35]
	v_mfma_f32_16x16x32_bf16 v[20:23], v[214:217], v[194:197], v[20:23]
	v_mfma_f32_16x16x32_bf16 v[16:19], v[222:225], v[194:197], v[16:19]
	v_mfma_f32_16x16x32_bf16 v[4:7], v[214:217], v[202:205], v[4:7]
	v_mfma_f32_16x16x32_bf16 v[0:3], v[222:225], v[202:205], v[0:3]
	v_add_u32_e32 v56, s79, v139
	s_barrier
	ds_read_b128 v[150:153], v56
	ds_read_b128 v[154:157], v56 offset:1024
	ds_read_b128 v[158:161], v56 offset:2048
	ds_read_b128 v[162:165], v56 offset:3072
	s_add_u32 s38, s38, 0x100000
	s_addc_u32 s39, s39, 0
	s_mov_b32 m0, s46
	v_lshl_add_u64 v[206:207], s[38:39], 0, v[134:135]
	ds_read_b128 v[166:169], v133 offset:32768
	ds_read_b128 v[170:173], v133 offset:33792
	ds_read_b128 v[182:185], v133 offset:34816
	ds_read_b128 v[186:189], v133 offset:35840
	ds_read_b128 v[190:193], v133 offset:36864
	ds_read_b128 v[194:197], v133 offset:37888
	ds_read_b128 v[198:201], v133 offset:38912
	ds_read_b128 v[202:205], v133 offset:39936
	global_load_lds_dwordx4 v[206:207], off
	s_mov_b32 m0, s47
	v_lshl_add_u64 v[206:207], s[38:39], 0, v[136:137]
	global_load_lds_dwordx4 v[206:207], off
	s_waitcnt lgkmcnt(8)
	s_barrier
	s_waitcnt lgkmcnt(0)
	v_mfma_f32_16x16x32_bf16 v[128:131], v[150:153], v[166:169], v[128:131]
	v_mfma_f32_16x16x32_bf16 v[124:127], v[158:161], v[166:169], v[124:127]
	v_mfma_f32_16x16x32_bf16 v[112:115], v[150:153], v[182:185], v[112:115]
	v_mfma_f32_16x16x32_bf16 v[108:111], v[158:161], v[182:185], v[108:111]
	v_mfma_f32_16x16x32_bf16 v[96:99], v[150:153], v[190:193], v[96:99]
	v_mfma_f32_16x16x32_bf16 v[92:95], v[158:161], v[190:193], v[92:95]
	v_mfma_f32_16x16x32_bf16 v[80:83], v[150:153], v[198:201], v[80:83]
	v_mfma_f32_16x16x32_bf16 v[76:79], v[158:161], v[198:201], v[76:79]
	v_mfma_f32_16x16x32_bf16 v[128:131], v[154:157], v[170:173], v[128:131]
	v_mfma_f32_16x16x32_bf16 v[124:127], v[162:165], v[170:173], v[124:127]
	v_mfma_f32_16x16x32_bf16 v[112:115], v[154:157], v[186:189], v[112:115]
	v_mfma_f32_16x16x32_bf16 v[108:111], v[162:165], v[186:189], v[108:111]
	v_mfma_f32_16x16x32_bf16 v[96:99], v[154:157], v[194:197], v[96:99]
	v_mfma_f32_16x16x32_bf16 v[92:95], v[162:165], v[194:197], v[92:95]
	v_mfma_f32_16x16x32_bf16 v[80:83], v[154:157], v[202:205], v[80:83]
	v_mfma_f32_16x16x32_bf16 v[76:79], v[162:165], v[202:205], v[76:79]
	s_barrier
	s_add_i32 s3, 0, 0x1c000
	s_add_i32 s38, s79, s41
	v_add_u32_e32 v56, s3, v139
	v_lshl_add_u64 v[174:175], v[174:175], 0, s[16:17]
	s_mov_b32 m0, s38
	ds_read_b128 v[206:209], v56
	ds_read_b128 v[214:217], v56 offset:1024
	ds_read_b128 v[218:221], v56 offset:2048
	ds_read_b128 v[222:225], v56 offset:3072
	global_load_lds_dwordx4 v[174:175], off
	s_add_i32 m0, s38, 0x2000
	v_lshl_add_u64 v[174:175], v[226:227], 0, s[16:17]
	global_load_lds_dwordx4 v[174:175], off
	s_barrier
	s_waitcnt lgkmcnt(0)
	v_mfma_f32_16x16x32_bf16 v[120:123], v[206:209], v[166:169], v[120:123]
	v_mfma_f32_16x16x32_bf16 v[116:119], v[218:221], v[166:169], v[116:119]
	v_mfma_f32_16x16x32_bf16 v[104:107], v[206:209], v[182:185], v[104:107]
	v_mfma_f32_16x16x32_bf16 v[100:103], v[218:221], v[182:185], v[100:103]
	v_mfma_f32_16x16x32_bf16 v[88:91], v[206:209], v[190:193], v[88:91]
	v_mfma_f32_16x16x32_bf16 v[84:87], v[218:221], v[190:193], v[84:87]
	v_mfma_f32_16x16x32_bf16 v[72:75], v[206:209], v[198:201], v[72:75]
	v_mfma_f32_16x16x32_bf16 v[68:71], v[218:221], v[198:201], v[68:71]
	v_mfma_f32_16x16x32_bf16 v[120:123], v[214:217], v[170:173], v[120:123]
	v_mfma_f32_16x16x32_bf16 v[116:119], v[222:225], v[170:173], v[116:119]
	v_mfma_f32_16x16x32_bf16 v[104:107], v[214:217], v[186:189], v[104:107]
	v_mfma_f32_16x16x32_bf16 v[100:103], v[222:225], v[186:189], v[100:103]
	v_mfma_f32_16x16x32_bf16 v[88:91], v[214:217], v[194:197], v[88:91]
	v_mfma_f32_16x16x32_bf16 v[84:87], v[222:225], v[194:197], v[84:87]
	v_mfma_f32_16x16x32_bf16 v[72:75], v[214:217], v[202:205], v[72:75]
	v_mfma_f32_16x16x32_bf16 v[68:71], v[222:225], v[202:205], v[68:71]
	s_mov_b32 m0, s67
	v_lshl_add_u64 v[174:175], v[228:229], 0, s[16:17]
	s_barrier
	ds_read_b128 v[166:169], v133 offset:49152
	ds_read_b128 v[170:173], v133 offset:50176
	ds_read_b128 v[182:185], v133 offset:51200
	ds_read_b128 v[186:189], v133 offset:52224
	ds_read_b128 v[190:193], v133 offset:53248
	ds_read_b128 v[194:197], v133 offset:54272
	ds_read_b128 v[198:201], v133 offset:55296
	ds_read_b128 v[202:205], v133 offset:56320
	global_load_lds_dwordx4 v[174:175], off
	s_mov_b32 m0, s68
	v_lshl_add_u64 v[174:175], v[230:231], 0, s[16:17]
	global_load_lds_dwordx4 v[174:175], off
	s_barrier
	s_waitcnt lgkmcnt(0)
	v_mfma_f32_16x16x32_bf16 v[64:67], v[150:153], v[166:169], v[64:67]
	v_mfma_f32_16x16x32_bf16 v[60:63], v[158:161], v[166:169], v[60:63]
	v_mfma_f32_16x16x32_bf16 v[44:47], v[150:153], v[182:185], v[44:47]
	v_mfma_f32_16x16x32_bf16 v[40:43], v[158:161], v[182:185], v[40:43]
	v_mfma_f32_16x16x32_bf16 v[28:31], v[150:153], v[190:193], v[28:31]
	v_mfma_f32_16x16x32_bf16 v[24:27], v[158:161], v[190:193], v[24:27]
	v_mfma_f32_16x16x32_bf16 v[12:15], v[150:153], v[198:201], v[12:15]
	v_mfma_f32_16x16x32_bf16 v[8:11], v[158:161], v[198:201], v[8:11]
	v_mfma_f32_16x16x32_bf16 v[64:67], v[154:157], v[170:173], v[64:67]
	v_mfma_f32_16x16x32_bf16 v[60:63], v[162:165], v[170:173], v[60:63]
	v_mfma_f32_16x16x32_bf16 v[44:47], v[154:157], v[186:189], v[44:47]
	v_mfma_f32_16x16x32_bf16 v[40:43], v[162:165], v[186:189], v[40:43]
	v_mfma_f32_16x16x32_bf16 v[28:31], v[154:157], v[194:197], v[28:31]
	v_mfma_f32_16x16x32_bf16 v[24:27], v[162:165], v[194:197], v[24:27]
	v_mfma_f32_16x16x32_bf16 v[12:15], v[154:157], v[202:205], v[12:15]
	v_mfma_f32_16x16x32_bf16 v[8:11], v[162:165], v[202:205], v[8:11]
	s_barrier
	s_add_u32 s36, s36, 0x100080
	s_addc_u32 s37, s37, 0
	s_add_i32 s3, s3, s41
	s_mov_b32 m0, s3
	v_lshl_add_u64 v[150:151], s[36:37], 0, v[134:135]
	global_load_lds_dwordx4 v[150:151], off
	s_add_i32 m0, s3, 0x2000
	v_lshl_add_u64 v[150:151], s[36:37], 0, v[136:137]
	global_load_lds_dwordx4 v[150:151], off
	s_waitcnt vmcnt(6)
	s_barrier
	v_mfma_f32_16x16x32_bf16 v[52:55], v[206:209], v[166:169], v[52:55]
	v_mfma_f32_16x16x32_bf16 v[48:51], v[218:221], v[166:169], v[48:51]
	v_mfma_f32_16x16x32_bf16 v[36:39], v[206:209], v[182:185], v[36:39]
	v_mfma_f32_16x16x32_bf16 v[32:35], v[218:221], v[182:185], v[32:35]
	v_mfma_f32_16x16x32_bf16 v[20:23], v[206:209], v[190:193], v[20:23]
	v_mfma_f32_16x16x32_bf16 v[16:19], v[218:221], v[190:193], v[16:19]
	v_mfma_f32_16x16x32_bf16 v[4:7], v[206:209], v[198:201], v[4:7]
	v_mfma_f32_16x16x32_bf16 v[0:3], v[218:221], v[198:201], v[0:3]
	v_mfma_f32_16x16x32_bf16 v[52:55], v[214:217], v[170:173], v[52:55]
	v_mfma_f32_16x16x32_bf16 v[48:51], v[222:225], v[170:173], v[48:51]
	v_mfma_f32_16x16x32_bf16 v[36:39], v[214:217], v[186:189], v[36:39]
	v_mfma_f32_16x16x32_bf16 v[32:35], v[222:225], v[186:189], v[32:35]
	v_mfma_f32_16x16x32_bf16 v[20:23], v[214:217], v[194:197], v[20:23]
	v_mfma_f32_16x16x32_bf16 v[16:19], v[222:225], v[194:197], v[16:19]
	v_mfma_f32_16x16x32_bf16 v[4:7], v[214:217], v[202:205], v[4:7]
	v_mfma_f32_16x16x32_bf16 v[0:3], v[222:225], v[202:205], v[0:3]
	s_add_u32 s34, s34, 0x100
	s_addc_u32 s35, s35, 0
	s_cmp_ge_u32 s89, s49
	s_barrier
	s_cbranch_scc0 .LBB0_640
